# norm routine also for the first norm phase (rows read from the x / ctx inputs)
# speedup vs baseline: 1.0149x; 1.0037x over previous
.LBB0_211:
	s_cmp_lt_i32 s78, 2
	s_cselect_b64 s[0:1], -1, 0
	s_cmp_gt_i32 s79, 1
	s_cselect_b64 s[2:3], -1, 0
	s_and_b64 s[0:1], s[0:1], s[2:3]
	s_andn2_b64 vcc, exec, s[0:1]
	s_cbranch_vccnz .LBB0_276
	s_cmp_lg_u32 s87, 0x100
	s_cbranch_scc1 .Lnr1_orig
	v_mbcnt_hi_u32_b32 v0, -1, v212
	v_and_b32_e32 v0, 63, v0
	v_lshlrev_b32_e32 v1, 5, v0
	v_lshlrev_b32_e32 v2, 4, v0
	v_mov_b32_e32 v9, 0x358637bd
	v_mov_b32_e32 v10, 0x260
	v_xor_b32_e32 v3, 1, v0
	v_lshlrev_b32_e32 v3, 2, v3
	v_xor_b32_e32 v4, 2, v0
	v_lshlrev_b32_e32 v4, 2, v4
	v_xor_b32_e32 v5, 4, v0
	v_lshlrev_b32_e32 v5, 2, v5
	v_xor_b32_e32 v6, 8, v0
	v_lshlrev_b32_e32 v6, 2, v6
	v_xor_b32_e32 v7, 16, v0
	v_lshlrev_b32_e32 v7, 2, v7
	v_xor_b32_e32 v8, 32, v0
	v_lshlrev_b32_e32 v8, 2, v8
	s_lshl_b32 s31, s96, 3
	s_add_u32 s31, s31, s93
	s_add_u32 s64, s76, 0xc989000
	s_addc_u32 s65, s77, 0
	s_add_u32 s66, s76, 0x11189000
	s_addc_u32 s67, s77, 0
	s_add_u32 s68, s76, 0xe000
	s_addc_u32 s69, s77, 0
	v_readlane_b32 s54, v244, 15
	v_readlane_b32 s55, v244, 16
	s_mov_b32 s23, -1
	v_readlane_b32 s70, v244, 3
	v_readlane_b32 s71, v244, 4
	v_readlane_b32 s82, v244, 7
	v_readlane_b32 s83, v244, 8
	s_mul_i32 s5, s31, 9
	s_lshr_b32 s5, s5, 1
	s_add_u32 s41, s31, 1
	s_mul_i32 s41, s41, 9
	s_lshr_b32 s41, s41, 1
	s_nop 0
	s_add_u32 s54, s54, 0x0
	s_addc_u32 s55, s55, 0
	s_add_u32 s56, s54, 0x1000
	s_addc_u32 s57, s55, 0
	s_cmp_ge_u32 s5, s41
	s_cbranch_scc1 .Lnr1_done
	global_load_dwordx4 v[20:23], v1, s[54:55] offset:0
	global_load_dwordx4 v[24:27], v1, s[54:55] offset:16
	global_load_dwordx4 v[28:31], v1, s[54:55] offset:2048
	global_load_dwordx4 v[32:35], v1, s[54:55] offset:2064
	global_load_dwordx4 v[36:39], v1, s[56:57] offset:0
	global_load_dwordx4 v[40:43], v1, s[56:57] offset:16
	global_load_dwordx4 v[44:47], v1, s[56:57] offset:2048
	global_load_dwordx4 v[48:51], v1, s[56:57] offset:2064
	s_cmp_ge_u32 s5, 0x900
	s_cselect_b32 s25, 1, 0
	s_cmp_ge_u32 s5, 0x1200
	s_cselect_b32 s35, 1, 0
	s_add_u32 s25, s25, s35
	s_cmp_ge_u32 s5, 0x1b00
	s_cselect_b32 s35, 1, 0
	s_add_u32 s25, s25, s35
	s_mul_i32 s27, s25, 0x900
	s_sub_u32 s27, s5, s27
	s_cmp_lt_u32 s27, 0x100
	s_cbranch_scc1 .Lnr1_xa0_5_c
	s_lshl_b32 s35, s25, 11
	s_add_u32 s35, s35, s27
	s_sub_u32 s35, s35, 0x100
	s_lshl_b32 s35, s35, 13
	s_add_u32 s2, s70, s35
	s_addc_u32 s3, s71, 0
	s_branch .Lnr1_xa0_5_e
.Lnr1_xa0_5_c:
	s_lshl_b32 s35, s25, 8
	s_add_u32 s35, s35, s27
	s_lshl_b32 s35, s35, 13
	s_add_u32 s2, s82, s35
	s_addc_u32 s3, s83, 0
.Lnr1_xa0_5_e:
	s_add_u32 s6, s2, 0x1000
	s_addc_u32 s7, s3, 0
	global_load_dwordx4 v[116:119], v1, s[2:3] offset:0
	global_load_dwordx4 v[120:123], v1, s[2:3] offset:16
	global_load_dwordx4 v[124:127], v1, s[2:3] offset:2048
	global_load_dwordx4 v[128:131], v1, s[2:3] offset:2064
	global_load_dwordx4 v[132:135], v1, s[6:7] offset:0
	global_load_dwordx4 v[136:139], v1, s[6:7] offset:16
	global_load_dwordx4 v[140:143], v1, s[6:7] offset:2048
	global_load_dwordx4 v[144:147], v1, s[6:7] offset:2064
	s_waitcnt vmcnt(8)
.Lnr1_loop:
	s_add_u32 s31, s5, 1
	s_cmp_ge_u32 s31, s41
	s_cbranch_scc1 .Lnr1_last0
	s_cmp_ge_u32 s31, 0x900
	s_cselect_b32 s25, 1, 0
	s_cmp_ge_u32 s31, 0x1200
	s_cselect_b32 s35, 1, 0
	s_add_u32 s25, s25, s35
	s_cmp_ge_u32 s31, 0x1b00
	s_cselect_b32 s35, 1, 0
	s_add_u32 s25, s25, s35
	s_mul_i32 s27, s25, 0x900
	s_sub_u32 s27, s31, s27
	s_cmp_lt_u32 s27, 0x100
	s_cbranch_scc1 .Lnr1_xa1_31_c
	s_lshl_b32 s35, s25, 11
	s_add_u32 s35, s35, s27
	s_sub_u32 s35, s35, 0x100
	s_lshl_b32 s35, s35, 13
	s_add_u32 s10, s70, s35
	s_addc_u32 s11, s71, 0
	s_branch .Lnr1_xa1_31_e
.Lnr1_xa1_31_c:
	s_lshl_b32 s35, s25, 8
	s_add_u32 s35, s35, s27
	s_lshl_b32 s35, s35, 13
	s_add_u32 s10, s82, s35
	s_addc_u32 s11, s83, 0
.Lnr1_xa1_31_e:
	s_add_u32 s32, s10, 0x1000
	s_addc_u32 s33, s11, 0
	global_load_dwordx4 v[148:151], v1, s[10:11] offset:0
	global_load_dwordx4 v[152:155], v1, s[10:11] offset:16
	global_load_dwordx4 v[156:159], v1, s[10:11] offset:2048
	global_load_dwordx4 v[160:163], v1, s[10:11] offset:2064
	global_load_dwordx4 v[164:167], v1, s[32:33] offset:0
	global_load_dwordx4 v[168:171], v1, s[32:33] offset:16
	global_load_dwordx4 v[172:175], v1, s[32:33] offset:2048
	global_load_dwordx4 v[176:179], v1, s[32:33] offset:2064
	s_cmp_ge_u32 s5, 0x900
	s_cselect_b32 s25, 1, 0
	s_cmp_ge_u32 s5, 0x1200
	s_cselect_b32 s35, 1, 0
	s_add_u32 s25, s25, s35
	s_cmp_ge_u32 s5, 0x1b00
	s_cselect_b32 s35, 1, 0
	s_add_u32 s25, s25, s35
	s_mul_i32 s27, s25, 0x900
	s_sub_u32 s27, s5, s27
	s_cmp_lt_u32 s27, 0x100
	s_cselect_b32 s20, 4, s25
	s_cmp_eq_u32 s20, s23
	s_cbranch_scc1 .Lnr1_0_0_same
	s_mov_b32 s23, s20
	s_mul_i32 s35, s20, 0xc000
	s_add_u32 s42, s68, s35
	s_addc_u32 s43, s69, 0
	s_add_u32 s44, s42, 0x1000
	s_addc_u32 s45, s43, 0
	global_load_dwordx4 v[52:55], v1, s[42:43] offset:0
	global_load_dwordx4 v[56:59], v1, s[42:43] offset:16
	global_load_dwordx4 v[60:63], v1, s[42:43] offset:2048
	global_load_dwordx4 v[64:67], v1, s[42:43] offset:2064
	global_load_dwordx4 v[68:71], v1, s[44:45] offset:0
	global_load_dwordx4 v[72:75], v1, s[44:45] offset:16
	global_load_dwordx4 v[76:79], v1, s[44:45] offset:2048
	global_load_dwordx4 v[80:83], v1, s[44:45] offset:2064
	s_add_u32 s42, s42, 0x2000
	s_addc_u32 s43, s43, 0
	s_add_u32 s44, s44, 0x2000
	s_addc_u32 s45, s45, 0
	global_load_dwordx4 v[84:87], v1, s[42:43] offset:0
	global_load_dwordx4 v[88:91], v1, s[42:43] offset:16
	global_load_dwordx4 v[92:95], v1, s[42:43] offset:2048
	global_load_dwordx4 v[96:99], v1, s[42:43] offset:2064
	global_load_dwordx4 v[100:103], v1, s[44:45] offset:0
	global_load_dwordx4 v[104:107], v1, s[44:45] offset:16
	global_load_dwordx4 v[108:111], v1, s[44:45] offset:2048
	global_load_dwordx4 v[112:115], v1, s[44:45] offset:2064
	s_waitcnt vmcnt(0)
	v_add_f32_e32 v84, 1.0, v84
	v_add_f32_e32 v85, 1.0, v85
	v_add_f32_e32 v86, 1.0, v86
	v_add_f32_e32 v87, 1.0, v87
	v_add_f32_e32 v88, 1.0, v88
	v_add_f32_e32 v89, 1.0, v89
	v_add_f32_e32 v90, 1.0, v90
	v_add_f32_e32 v91, 1.0, v91
	v_add_f32_e32 v92, 1.0, v92
	v_add_f32_e32 v93, 1.0, v93
	v_add_f32_e32 v94, 1.0, v94
	v_add_f32_e32 v95, 1.0, v95
	v_add_f32_e32 v96, 1.0, v96
	v_add_f32_e32 v97, 1.0, v97
	v_add_f32_e32 v98, 1.0, v98
	v_add_f32_e32 v99, 1.0, v99
	v_add_f32_e32 v100, 1.0, v100
	v_add_f32_e32 v101, 1.0, v101
	v_add_f32_e32 v102, 1.0, v102
	v_add_f32_e32 v103, 1.0, v103
	v_add_f32_e32 v104, 1.0, v104
	v_add_f32_e32 v105, 1.0, v105
	v_add_f32_e32 v106, 1.0, v106
	v_add_f32_e32 v107, 1.0, v107
	v_add_f32_e32 v108, 1.0, v108
	v_add_f32_e32 v109, 1.0, v109
	v_add_f32_e32 v110, 1.0, v110
	v_add_f32_e32 v111, 1.0, v111
	v_add_f32_e32 v112, 1.0, v112
	v_add_f32_e32 v113, 1.0, v113
	v_add_f32_e32 v114, 1.0, v114
	v_add_f32_e32 v115, 1.0, v115
.Lnr1_0_0_same:
	s_waitcnt vmcnt(12)
	v_mul_f32_e32 v11, v116, v116
	v_fmac_f32_e32 v11, v117, v117
	v_fmac_f32_e32 v11, v118, v118
	v_fmac_f32_e32 v11, v119, v119
	v_fmac_f32_e32 v11, v120, v120
	v_fmac_f32_e32 v11, v121, v121
	v_fmac_f32_e32 v11, v122, v122
	v_fmac_f32_e32 v11, v123, v123
	v_fmac_f32_e32 v11, v124, v124
	v_fmac_f32_e32 v11, v125, v125
	v_fmac_f32_e32 v11, v126, v126
	v_fmac_f32_e32 v11, v127, v127
	v_fmac_f32_e32 v11, v128, v128
	v_fmac_f32_e32 v11, v129, v129
	v_fmac_f32_e32 v11, v130, v130
	v_fmac_f32_e32 v11, v131, v131
	v_fmac_f32_e32 v11, v132, v132
	v_fmac_f32_e32 v11, v133, v133
	v_fmac_f32_e32 v11, v134, v134
	v_fmac_f32_e32 v11, v135, v135
	v_fmac_f32_e32 v11, v136, v136
	v_fmac_f32_e32 v11, v137, v137
	v_fmac_f32_e32 v11, v138, v138
	v_fmac_f32_e32 v11, v139, v139
	v_fmac_f32_e32 v11, v140, v140
	v_fmac_f32_e32 v11, v141, v141
	v_fmac_f32_e32 v11, v142, v142
	v_fmac_f32_e32 v11, v143, v143
	v_fmac_f32_e32 v11, v144, v144
	v_fmac_f32_e32 v11, v145, v145
	v_fmac_f32_e32 v11, v146, v146
	v_fmac_f32_e32 v11, v147, v147
	ds_bpermute_b32 v12, v3, v11
	s_waitcnt lgkmcnt(0)
	v_add_f32_e32 v11, v11, v12
	ds_bpermute_b32 v12, v4, v11
	s_waitcnt lgkmcnt(0)
	v_add_f32_e32 v11, v11, v12
	ds_bpermute_b32 v12, v5, v11
	s_waitcnt lgkmcnt(0)
	v_add_f32_e32 v11, v11, v12
	ds_bpermute_b32 v12, v6, v11
	s_waitcnt lgkmcnt(0)
	v_add_f32_e32 v11, v11, v12
	ds_bpermute_b32 v12, v7, v11
	s_waitcnt lgkmcnt(0)
	v_add_f32_e32 v11, v11, v12
	ds_bpermute_b32 v12, v8, v11
	s_waitcnt lgkmcnt(0)
	v_add_f32_e32 v11, v11, v12
	v_fmamk_f32 v11, v11, 0x3a000000, v9
	v_mul_f32_e32 v13, 0x4f800000, v11
	v_cmp_gt_f32_e32 vcc, 0xf800000, v11
	s_nop 1
	v_cndmask_b32_e32 v11, v11, v13, vcc
	v_sqrt_f32_e32 v13, v11
	s_nop 0
	v_add_u32_e32 v14, -1, v13
	v_add_u32_e32 v15, 1, v13
	v_fma_f32 v16, -v14, v13, v11
	v_fma_f32 v17, -v15, v13, v11
	v_cmp_ge_f32_e64 s[0:1], 0, v16
	s_nop 1
	v_cndmask_b32_e64 v13, v13, v14, s[0:1]
	v_cmp_lt_f32_e64 s[0:1], 0, v17
	s_nop 1
	v_cndmask_b32_e64 v13, v13, v15, s[0:1]
	v_mul_f32_e32 v14, 0x37800000, v13
	v_cndmask_b32_e32 v13, v13, v14, vcc
	v_cmp_class_f32_e32 vcc, v11, v10
	s_nop 1
	v_cndmask_b32_e32 v11, v13, v11, vcc
	v_div_scale_f32 v13, s[0:1], v11, v11, 1.0
	v_rcp_f32_e32 v15, v13
	v_div_scale_f32 v14, vcc, 1.0, v11, 1.0
	v_fma_f32 v16, -v13, v15, 1.0
	v_fmac_f32_e32 v15, v16, v15
	v_mul_f32_e32 v16, v14, v15
	v_fma_f32 v17, -v13, v16, v14
	v_fmac_f32_e32 v16, v17, v15
	v_fma_f32 v13, -v13, v16, v14
	v_div_fmas_f32 v13, v13, v15, v16
	v_div_fixup_f32 v11, v13, v11, 1.0
	s_lshl_b32 s35, s5, 12
	s_add_u32 s62, s66, s35
	s_addc_u32 s63, s67, 0
	v_mul_f32_e32 v116, v116, v11
	v_mul_f32_e32 v116, v20, v116
	v_fma_f32 v116, v84, v116, v52
	v_mul_f32_e32 v117, v117, v11
	v_mul_f32_e32 v117, v21, v117
	v_fma_f32 v117, v85, v117, v53
	v_mul_f32_e32 v118, v118, v11
	v_mul_f32_e32 v118, v22, v118
	v_fma_f32 v118, v86, v118, v54
	v_mul_f32_e32 v119, v119, v11
	v_mul_f32_e32 v119, v23, v119
	v_fma_f32 v119, v87, v119, v55
	v_mul_f32_e32 v120, v120, v11
	v_mul_f32_e32 v120, v24, v120
	v_fma_f32 v120, v88, v120, v56
	v_mul_f32_e32 v121, v121, v11
	v_mul_f32_e32 v121, v25, v121
	v_fma_f32 v121, v89, v121, v57
	v_mul_f32_e32 v122, v122, v11
	v_mul_f32_e32 v122, v26, v122
	v_fma_f32 v122, v90, v122, v58
	v_mul_f32_e32 v123, v123, v11
	v_mul_f32_e32 v123, v27, v123
	v_fma_f32 v123, v91, v123, v59
	v_cvt_pk_bf16_f32 v180, v116, v117
	v_cvt_pk_bf16_f32 v181, v118, v119
	v_cvt_pk_bf16_f32 v182, v120, v121
	v_cvt_pk_bf16_f32 v183, v122, v123
	global_store_dwordx4 v2, v[180:183], s[62:63] offset:0 sc1
	v_mul_f32_e32 v124, v124, v11
	v_mul_f32_e32 v124, v28, v124
	v_fma_f32 v124, v92, v124, v60
	v_mul_f32_e32 v125, v125, v11
	v_mul_f32_e32 v125, v29, v125
	v_fma_f32 v125, v93, v125, v61
	v_mul_f32_e32 v126, v126, v11
	v_mul_f32_e32 v126, v30, v126
	v_fma_f32 v126, v94, v126, v62
	v_mul_f32_e32 v127, v127, v11
	v_mul_f32_e32 v127, v31, v127
	v_fma_f32 v127, v95, v127, v63
	v_mul_f32_e32 v128, v128, v11
	v_mul_f32_e32 v128, v32, v128
	v_fma_f32 v128, v96, v128, v64
	v_mul_f32_e32 v129, v129, v11
	v_mul_f32_e32 v129, v33, v129
	v_fma_f32 v129, v97, v129, v65
	v_mul_f32_e32 v130, v130, v11
	v_mul_f32_e32 v130, v34, v130
	v_fma_f32 v130, v98, v130, v66
	v_mul_f32_e32 v131, v131, v11
	v_mul_f32_e32 v131, v35, v131
	v_fma_f32 v131, v99, v131, v67
	v_cvt_pk_bf16_f32 v184, v124, v125
	v_cvt_pk_bf16_f32 v185, v126, v127
	v_cvt_pk_bf16_f32 v186, v128, v129
	v_cvt_pk_bf16_f32 v187, v130, v131
	global_store_dwordx4 v2, v[184:187], s[62:63] offset:1024 sc1
	v_mul_f32_e32 v132, v132, v11
	v_mul_f32_e32 v132, v36, v132
	v_fma_f32 v132, v100, v132, v68
	v_mul_f32_e32 v133, v133, v11
	v_mul_f32_e32 v133, v37, v133
	v_fma_f32 v133, v101, v133, v69
	v_mul_f32_e32 v134, v134, v11
	v_mul_f32_e32 v134, v38, v134
	v_fma_f32 v134, v102, v134, v70
	v_mul_f32_e32 v135, v135, v11
	v_mul_f32_e32 v135, v39, v135
	v_fma_f32 v135, v103, v135, v71
	v_mul_f32_e32 v136, v136, v11
	v_mul_f32_e32 v136, v40, v136
	v_fma_f32 v136, v104, v136, v72
	v_mul_f32_e32 v137, v137, v11
	v_mul_f32_e32 v137, v41, v137
	v_fma_f32 v137, v105, v137, v73
	v_mul_f32_e32 v138, v138, v11
	v_mul_f32_e32 v138, v42, v138
	v_fma_f32 v138, v106, v138, v74
	v_mul_f32_e32 v139, v139, v11
	v_mul_f32_e32 v139, v43, v139
	v_fma_f32 v139, v107, v139, v75
	v_cvt_pk_bf16_f32 v188, v132, v133
	v_cvt_pk_bf16_f32 v189, v134, v135
	v_cvt_pk_bf16_f32 v190, v136, v137
	v_cvt_pk_bf16_f32 v191, v138, v139
	global_store_dwordx4 v2, v[188:191], s[62:63] offset:2048 sc1
	v_mul_f32_e32 v140, v140, v11
	v_mul_f32_e32 v140, v44, v140
	v_fma_f32 v140, v108, v140, v76
	v_mul_f32_e32 v141, v141, v11
	v_mul_f32_e32 v141, v45, v141
	v_fma_f32 v141, v109, v141, v77
	v_mul_f32_e32 v142, v142, v11
	v_mul_f32_e32 v142, v46, v142
	v_fma_f32 v142, v110, v142, v78
	v_mul_f32_e32 v143, v143, v11
	v_mul_f32_e32 v143, v47, v143
	v_fma_f32 v143, v111, v143, v79
	v_mul_f32_e32 v144, v144, v11
	v_mul_f32_e32 v144, v48, v144
	v_fma_f32 v144, v112, v144, v80
	v_mul_f32_e32 v145, v145, v11
	v_mul_f32_e32 v145, v49, v145
	v_fma_f32 v145, v113, v145, v81
	v_mul_f32_e32 v146, v146, v11
	v_mul_f32_e32 v146, v50, v146
	v_fma_f32 v146, v114, v146, v82
	v_mul_f32_e32 v147, v147, v11
	v_mul_f32_e32 v147, v51, v147
	v_fma_f32 v147, v115, v147, v83
	v_cvt_pk_bf16_f32 v192, v140, v141
	v_cvt_pk_bf16_f32 v193, v142, v143
	v_cvt_pk_bf16_f32 v194, v144, v145
	v_cvt_pk_bf16_f32 v195, v146, v147
	global_store_dwordx4 v2, v[192:195], s[62:63] offset:3072 sc1
	s_add_u32 s5, s5, 1
	s_add_u32 s31, s5, 1
	s_cmp_ge_u32 s31, s41
	s_cbranch_scc1 .Lnr1_last1
	s_cmp_ge_u32 s31, 0x900
	s_cselect_b32 s25, 1, 0
	s_cmp_ge_u32 s31, 0x1200
	s_cselect_b32 s35, 1, 0
	s_add_u32 s25, s25, s35
	s_cmp_ge_u32 s31, 0x1b00
	s_cselect_b32 s35, 1, 0
	s_add_u32 s25, s25, s35
	s_mul_i32 s27, s25, 0x900
	s_sub_u32 s27, s31, s27
	s_cmp_lt_u32 s27, 0x100
	s_cbranch_scc1 .Lnr1_xa0_31_c
	s_lshl_b32 s35, s25, 11
	s_add_u32 s35, s35, s27
	s_sub_u32 s35, s35, 0x100
	s_lshl_b32 s35, s35, 13
	s_add_u32 s2, s70, s35
	s_addc_u32 s3, s71, 0
	s_branch .Lnr1_xa0_31_e

.Lnr1_xa0_31_e:
	s_add_u32 s6, s2, 0x1000
	s_addc_u32 s7, s3, 0
	global_load_dwordx4 v[116:119], v1, s[2:3] offset:0
	global_load_dwordx4 v[120:123], v1, s[2:3] offset:16
	global_load_dwordx4 v[124:127], v1, s[2:3] offset:2048
	global_load_dwordx4 v[128:131], v1, s[2:3] offset:2064
	global_load_dwordx4 v[132:135], v1, s[6:7] offset:0
	global_load_dwordx4 v[136:139], v1, s[6:7] offset:16
	global_load_dwordx4 v[140:143], v1, s[6:7] offset:2048
	global_load_dwordx4 v[144:147], v1, s[6:7] offset:2064
	s_cmp_ge_u32 s5, 0x900
	s_cselect_b32 s25, 1, 0
	s_cmp_ge_u32 s5, 0x1200
	s_cselect_b32 s35, 1, 0
	s_add_u32 s25, s25, s35
	s_cmp_ge_u32 s5, 0x1b00
	s_cselect_b32 s35, 1, 0
	s_add_u32 s25, s25, s35
	s_mul_i32 s27, s25, 0x900
	s_sub_u32 s27, s5, s27
	s_cmp_lt_u32 s27, 0x100
	s_cselect_b32 s20, 4, s25
	s_cmp_eq_u32 s20, s23
	s_cbranch_scc1 .Lnr1_1_0_same
	s_mov_b32 s23, s20
	s_mul_i32 s35, s20, 0xc000
	s_add_u32 s42, s68, s35
	s_addc_u32 s43, s69, 0
	s_add_u32 s44, s42, 0x1000
	s_addc_u32 s45, s43, 0
	global_load_dwordx4 v[52:55], v1, s[42:43] offset:0
	global_load_dwordx4 v[56:59], v1, s[42:43] offset:16
	global_load_dwordx4 v[60:63], v1, s[42:43] offset:2048
	global_load_dwordx4 v[64:67], v1, s[42:43] offset:2064
	global_load_dwordx4 v[68:71], v1, s[44:45] offset:0
	global_load_dwordx4 v[72:75], v1, s[44:45] offset:16
	global_load_dwordx4 v[76:79], v1, s[44:45] offset:2048
	global_load_dwordx4 v[80:83], v1, s[44:45] offset:2064
	s_add_u32 s42, s42, 0x2000
	s_addc_u32 s43, s43, 0
	s_add_u32 s44, s44, 0x2000
	s_addc_u32 s45, s45, 0
	global_load_dwordx4 v[84:87], v1, s[42:43] offset:0
	global_load_dwordx4 v[88:91], v1, s[42:43] offset:16
	global_load_dwordx4 v[92:95], v1, s[42:43] offset:2048
	global_load_dwordx4 v[96:99], v1, s[42:43] offset:2064
	global_load_dwordx4 v[100:103], v1, s[44:45] offset:0
	global_load_dwordx4 v[104:107], v1, s[44:45] offset:16
	global_load_dwordx4 v[108:111], v1, s[44:45] offset:2048
	global_load_dwordx4 v[112:115], v1, s[44:45] offset:2064
	s_waitcnt vmcnt(0)
	v_add_f32_e32 v84, 1.0, v84
	v_add_f32_e32 v85, 1.0, v85
	v_add_f32_e32 v86, 1.0, v86
	v_add_f32_e32 v87, 1.0, v87
	v_add_f32_e32 v88, 1.0, v88
	v_add_f32_e32 v89, 1.0, v89
	v_add_f32_e32 v90, 1.0, v90
	v_add_f32_e32 v91, 1.0, v91
	v_add_f32_e32 v92, 1.0, v92
	v_add_f32_e32 v93, 1.0, v93
	v_add_f32_e32 v94, 1.0, v94
	v_add_f32_e32 v95, 1.0, v95
	v_add_f32_e32 v96, 1.0, v96
	v_add_f32_e32 v97, 1.0, v97
	v_add_f32_e32 v98, 1.0, v98
	v_add_f32_e32 v99, 1.0, v99
	v_add_f32_e32 v100, 1.0, v100
	v_add_f32_e32 v101, 1.0, v101
	v_add_f32_e32 v102, 1.0, v102
	v_add_f32_e32 v103, 1.0, v103
	v_add_f32_e32 v104, 1.0, v104
	v_add_f32_e32 v105, 1.0, v105
	v_add_f32_e32 v106, 1.0, v106
	v_add_f32_e32 v107, 1.0, v107
	v_add_f32_e32 v108, 1.0, v108
	v_add_f32_e32 v109, 1.0, v109
	v_add_f32_e32 v110, 1.0, v110
	v_add_f32_e32 v111, 1.0, v111
	v_add_f32_e32 v112, 1.0, v112
	v_add_f32_e32 v113, 1.0, v113
	v_add_f32_e32 v114, 1.0, v114
	v_add_f32_e32 v115, 1.0, v115
.Lnr1_1_0_same:
	s_waitcnt vmcnt(12)
	v_mul_f32_e32 v11, v148, v148
	v_fmac_f32_e32 v11, v149, v149
	v_fmac_f32_e32 v11, v150, v150
	v_fmac_f32_e32 v11, v151, v151
	v_fmac_f32_e32 v11, v152, v152
	v_fmac_f32_e32 v11, v153, v153
	v_fmac_f32_e32 v11, v154, v154
	v_fmac_f32_e32 v11, v155, v155
	v_fmac_f32_e32 v11, v156, v156
	v_fmac_f32_e32 v11, v157, v157
	v_fmac_f32_e32 v11, v158, v158
	v_fmac_f32_e32 v11, v159, v159
	v_fmac_f32_e32 v11, v160, v160
	v_fmac_f32_e32 v11, v161, v161
	v_fmac_f32_e32 v11, v162, v162
	v_fmac_f32_e32 v11, v163, v163
	v_fmac_f32_e32 v11, v164, v164
	v_fmac_f32_e32 v11, v165, v165
	v_fmac_f32_e32 v11, v166, v166
	v_fmac_f32_e32 v11, v167, v167
	v_fmac_f32_e32 v11, v168, v168
	v_fmac_f32_e32 v11, v169, v169
	v_fmac_f32_e32 v11, v170, v170
	v_fmac_f32_e32 v11, v171, v171
	v_fmac_f32_e32 v11, v172, v172
	v_fmac_f32_e32 v11, v173, v173
	v_fmac_f32_e32 v11, v174, v174
	v_fmac_f32_e32 v11, v175, v175
	v_fmac_f32_e32 v11, v176, v176
	v_fmac_f32_e32 v11, v177, v177
	v_fmac_f32_e32 v11, v178, v178
	v_fmac_f32_e32 v11, v179, v179
	ds_bpermute_b32 v12, v3, v11
	s_waitcnt lgkmcnt(0)
	v_add_f32_e32 v11, v11, v12
	ds_bpermute_b32 v12, v4, v11
	s_waitcnt lgkmcnt(0)
	v_add_f32_e32 v11, v11, v12
	ds_bpermute_b32 v12, v5, v11
	s_waitcnt lgkmcnt(0)
	v_add_f32_e32 v11, v11, v12
	ds_bpermute_b32 v12, v6, v11
	s_waitcnt lgkmcnt(0)
	v_add_f32_e32 v11, v11, v12
	ds_bpermute_b32 v12, v7, v11
	s_waitcnt lgkmcnt(0)
	v_add_f32_e32 v11, v11, v12
	ds_bpermute_b32 v12, v8, v11
	s_waitcnt lgkmcnt(0)
	v_add_f32_e32 v11, v11, v12
	v_fmamk_f32 v11, v11, 0x3a000000, v9
	v_mul_f32_e32 v13, 0x4f800000, v11
	v_cmp_gt_f32_e32 vcc, 0xf800000, v11
	s_nop 1
	v_cndmask_b32_e32 v11, v11, v13, vcc
	v_sqrt_f32_e32 v13, v11
	s_nop 0
	v_add_u32_e32 v14, -1, v13
	v_add_u32_e32 v15, 1, v13
	v_fma_f32 v16, -v14, v13, v11
	v_fma_f32 v17, -v15, v13, v11
	v_cmp_ge_f32_e64 s[0:1], 0, v16
	s_nop 1
	v_cndmask_b32_e64 v13, v13, v14, s[0:1]
	v_cmp_lt_f32_e64 s[0:1], 0, v17
	s_nop 1
	v_cndmask_b32_e64 v13, v13, v15, s[0:1]
	v_mul_f32_e32 v14, 0x37800000, v13
	v_cndmask_b32_e32 v13, v13, v14, vcc
	v_cmp_class_f32_e32 vcc, v11, v10
	s_nop 1
	v_cndmask_b32_e32 v11, v13, v11, vcc
	v_div_scale_f32 v13, s[0:1], v11, v11, 1.0
	v_rcp_f32_e32 v15, v13
	v_div_scale_f32 v14, vcc, 1.0, v11, 1.0
	v_fma_f32 v16, -v13, v15, 1.0
	v_fmac_f32_e32 v15, v16, v15
	v_mul_f32_e32 v16, v14, v15
	v_fma_f32 v17, -v13, v16, v14
	v_fmac_f32_e32 v16, v17, v15
	v_fma_f32 v13, -v13, v16, v14
	v_div_fmas_f32 v13, v13, v15, v16
	v_div_fixup_f32 v11, v13, v11, 1.0
	s_lshl_b32 s35, s5, 12
	s_add_u32 s62, s66, s35
	s_addc_u32 s63, s67, 0
	v_mul_f32_e32 v148, v148, v11
	v_mul_f32_e32 v148, v20, v148
	v_fma_f32 v148, v84, v148, v52
	v_mul_f32_e32 v149, v149, v11
	v_mul_f32_e32 v149, v21, v149
	v_fma_f32 v149, v85, v149, v53
	v_mul_f32_e32 v150, v150, v11
	v_mul_f32_e32 v150, v22, v150
	v_fma_f32 v150, v86, v150, v54
	v_mul_f32_e32 v151, v151, v11
	v_mul_f32_e32 v151, v23, v151
	v_fma_f32 v151, v87, v151, v55
	v_mul_f32_e32 v152, v152, v11
	v_mul_f32_e32 v152, v24, v152
	v_fma_f32 v152, v88, v152, v56
	v_mul_f32_e32 v153, v153, v11
	v_mul_f32_e32 v153, v25, v153
	v_fma_f32 v153, v89, v153, v57
	v_mul_f32_e32 v154, v154, v11
	v_mul_f32_e32 v154, v26, v154
	v_fma_f32 v154, v90, v154, v58
	v_mul_f32_e32 v155, v155, v11
	v_mul_f32_e32 v155, v27, v155
	v_fma_f32 v155, v91, v155, v59
	v_cvt_pk_bf16_f32 v180, v148, v149
	v_cvt_pk_bf16_f32 v181, v150, v151
	v_cvt_pk_bf16_f32 v182, v152, v153
	v_cvt_pk_bf16_f32 v183, v154, v155
	global_store_dwordx4 v2, v[180:183], s[62:63] offset:0 sc1
	v_mul_f32_e32 v156, v156, v11
	v_mul_f32_e32 v156, v28, v156
	v_fma_f32 v156, v92, v156, v60
	v_mul_f32_e32 v157, v157, v11
	v_mul_f32_e32 v157, v29, v157
	v_fma_f32 v157, v93, v157, v61
	v_mul_f32_e32 v158, v158, v11
	v_mul_f32_e32 v158, v30, v158
	v_fma_f32 v158, v94, v158, v62
	v_mul_f32_e32 v159, v159, v11
	v_mul_f32_e32 v159, v31, v159
	v_fma_f32 v159, v95, v159, v63
	v_mul_f32_e32 v160, v160, v11
	v_mul_f32_e32 v160, v32, v160
	v_fma_f32 v160, v96, v160, v64
	v_mul_f32_e32 v161, v161, v11
	v_mul_f32_e32 v161, v33, v161
	v_fma_f32 v161, v97, v161, v65
	v_mul_f32_e32 v162, v162, v11
	v_mul_f32_e32 v162, v34, v162
	v_fma_f32 v162, v98, v162, v66
	v_mul_f32_e32 v163, v163, v11
	v_mul_f32_e32 v163, v35, v163
	v_fma_f32 v163, v99, v163, v67
	v_cvt_pk_bf16_f32 v184, v156, v157
	v_cvt_pk_bf16_f32 v185, v158, v159
	v_cvt_pk_bf16_f32 v186, v160, v161
	v_cvt_pk_bf16_f32 v187, v162, v163
	global_store_dwordx4 v2, v[184:187], s[62:63] offset:1024 sc1
	v_mul_f32_e32 v164, v164, v11
	v_mul_f32_e32 v164, v36, v164
	v_fma_f32 v164, v100, v164, v68
	v_mul_f32_e32 v165, v165, v11
	v_mul_f32_e32 v165, v37, v165
	v_fma_f32 v165, v101, v165, v69
	v_mul_f32_e32 v166, v166, v11
	v_mul_f32_e32 v166, v38, v166
	v_fma_f32 v166, v102, v166, v70
	v_mul_f32_e32 v167, v167, v11
	v_mul_f32_e32 v167, v39, v167
	v_fma_f32 v167, v103, v167, v71
	v_mul_f32_e32 v168, v168, v11
	v_mul_f32_e32 v168, v40, v168
	v_fma_f32 v168, v104, v168, v72
	v_mul_f32_e32 v169, v169, v11
	v_mul_f32_e32 v169, v41, v169
	v_fma_f32 v169, v105, v169, v73
	v_mul_f32_e32 v170, v170, v11
	v_mul_f32_e32 v170, v42, v170
	v_fma_f32 v170, v106, v170, v74
	v_mul_f32_e32 v171, v171, v11
	v_mul_f32_e32 v171, v43, v171
	v_fma_f32 v171, v107, v171, v75
	v_cvt_pk_bf16_f32 v188, v164, v165
	v_cvt_pk_bf16_f32 v189, v166, v167
	v_cvt_pk_bf16_f32 v190, v168, v169
	v_cvt_pk_bf16_f32 v191, v170, v171
	global_store_dwordx4 v2, v[188:191], s[62:63] offset:2048 sc1
	v_mul_f32_e32 v172, v172, v11
	v_mul_f32_e32 v172, v44, v172
	v_fma_f32 v172, v108, v172, v76
	v_mul_f32_e32 v173, v173, v11
	v_mul_f32_e32 v173, v45, v173
	v_fma_f32 v173, v109, v173, v77
	v_mul_f32_e32 v174, v174, v11
	v_mul_f32_e32 v174, v46, v174
	v_fma_f32 v174, v110, v174, v78
	v_mul_f32_e32 v175, v175, v11
	v_mul_f32_e32 v175, v47, v175
	v_fma_f32 v175, v111, v175, v79
	v_mul_f32_e32 v176, v176, v11
	v_mul_f32_e32 v176, v48, v176
	v_fma_f32 v176, v112, v176, v80
	v_mul_f32_e32 v177, v177, v11
	v_mul_f32_e32 v177, v49, v177
	v_fma_f32 v177, v113, v177, v81
	v_mul_f32_e32 v178, v178, v11
	v_mul_f32_e32 v178, v50, v178
	v_fma_f32 v178, v114, v178, v82
	v_mul_f32_e32 v179, v179, v11
	v_mul_f32_e32 v179, v51, v179
	v_fma_f32 v179, v115, v179, v83
	v_cvt_pk_bf16_f32 v192, v172, v173
	v_cvt_pk_bf16_f32 v193, v174, v175
	v_cvt_pk_bf16_f32 v194, v176, v177
	v_cvt_pk_bf16_f32 v195, v178, v179
	global_store_dwordx4 v2, v[192:195], s[62:63] offset:3072 sc1
	s_add_u32 s5, s5, 1
	s_branch .Lnr1_loop
.Lnr1_last0:
	s_cmp_ge_u32 s5, 0x900
	s_cselect_b32 s25, 1, 0
	s_cmp_ge_u32 s5, 0x1200
	s_cselect_b32 s35, 1, 0
	s_add_u32 s25, s25, s35
	s_cmp_ge_u32 s5, 0x1b00
	s_cselect_b32 s35, 1, 0
	s_add_u32 s25, s25, s35
	s_mul_i32 s27, s25, 0x900
	s_sub_u32 s27, s5, s27
	s_cmp_lt_u32 s27, 0x100
	s_cselect_b32 s20, 4, s25
	s_cmp_eq_u32 s20, s23
	s_cbranch_scc1 .Lnr1_0_1_same
	s_mov_b32 s23, s20
	s_mul_i32 s35, s20, 0xc000
	s_add_u32 s42, s68, s35
	s_addc_u32 s43, s69, 0
	s_add_u32 s44, s42, 0x1000
	s_addc_u32 s45, s43, 0
	global_load_dwordx4 v[52:55], v1, s[42:43] offset:0
	global_load_dwordx4 v[56:59], v1, s[42:43] offset:16
	global_load_dwordx4 v[60:63], v1, s[42:43] offset:2048
	global_load_dwordx4 v[64:67], v1, s[42:43] offset:2064
	global_load_dwordx4 v[68:71], v1, s[44:45] offset:0
	global_load_dwordx4 v[72:75], v1, s[44:45] offset:16
	global_load_dwordx4 v[76:79], v1, s[44:45] offset:2048
	global_load_dwordx4 v[80:83], v1, s[44:45] offset:2064
	s_add_u32 s42, s42, 0x2000
	s_addc_u32 s43, s43, 0
	s_add_u32 s44, s44, 0x2000
	s_addc_u32 s45, s45, 0
	global_load_dwordx4 v[84:87], v1, s[42:43] offset:0
	global_load_dwordx4 v[88:91], v1, s[42:43] offset:16
	global_load_dwordx4 v[92:95], v1, s[42:43] offset:2048
	global_load_dwordx4 v[96:99], v1, s[42:43] offset:2064
	global_load_dwordx4 v[100:103], v1, s[44:45] offset:0
	global_load_dwordx4 v[104:107], v1, s[44:45] offset:16
	global_load_dwordx4 v[108:111], v1, s[44:45] offset:2048
	global_load_dwordx4 v[112:115], v1, s[44:45] offset:2064
	s_waitcnt vmcnt(0)
	v_add_f32_e32 v84, 1.0, v84
	v_add_f32_e32 v85, 1.0, v85
	v_add_f32_e32 v86, 1.0, v86
	v_add_f32_e32 v87, 1.0, v87
	v_add_f32_e32 v88, 1.0, v88
	v_add_f32_e32 v89, 1.0, v89
	v_add_f32_e32 v90, 1.0, v90
	v_add_f32_e32 v91, 1.0, v91
	v_add_f32_e32 v92, 1.0, v92
	v_add_f32_e32 v93, 1.0, v93
	v_add_f32_e32 v94, 1.0, v94
	v_add_f32_e32 v95, 1.0, v95
	v_add_f32_e32 v96, 1.0, v96
	v_add_f32_e32 v97, 1.0, v97
	v_add_f32_e32 v98, 1.0, v98
	v_add_f32_e32 v99, 1.0, v99
	v_add_f32_e32 v100, 1.0, v100
	v_add_f32_e32 v101, 1.0, v101
	v_add_f32_e32 v102, 1.0, v102
	v_add_f32_e32 v103, 1.0, v103
	v_add_f32_e32 v104, 1.0, v104
	v_add_f32_e32 v105, 1.0, v105
	v_add_f32_e32 v106, 1.0, v106
	v_add_f32_e32 v107, 1.0, v107
	v_add_f32_e32 v108, 1.0, v108
	v_add_f32_e32 v109, 1.0, v109
	v_add_f32_e32 v110, 1.0, v110
	v_add_f32_e32 v111, 1.0, v111
	v_add_f32_e32 v112, 1.0, v112
	v_add_f32_e32 v113, 1.0, v113
	v_add_f32_e32 v114, 1.0, v114
	v_add_f32_e32 v115, 1.0, v115
.Lnr1_0_1_same:
	s_waitcnt vmcnt(4)
	v_mul_f32_e32 v11, v116, v116
	v_fmac_f32_e32 v11, v117, v117
	v_fmac_f32_e32 v11, v118, v118
	v_fmac_f32_e32 v11, v119, v119
	v_fmac_f32_e32 v11, v120, v120
	v_fmac_f32_e32 v11, v121, v121
	v_fmac_f32_e32 v11, v122, v122
	v_fmac_f32_e32 v11, v123, v123
	v_fmac_f32_e32 v11, v124, v124
	v_fmac_f32_e32 v11, v125, v125
	v_fmac_f32_e32 v11, v126, v126
	v_fmac_f32_e32 v11, v127, v127
	v_fmac_f32_e32 v11, v128, v128
	v_fmac_f32_e32 v11, v129, v129
	v_fmac_f32_e32 v11, v130, v130
	v_fmac_f32_e32 v11, v131, v131
	v_fmac_f32_e32 v11, v132, v132
	v_fmac_f32_e32 v11, v133, v133
	v_fmac_f32_e32 v11, v134, v134
	v_fmac_f32_e32 v11, v135, v135
	v_fmac_f32_e32 v11, v136, v136
	v_fmac_f32_e32 v11, v137, v137
	v_fmac_f32_e32 v11, v138, v138
	v_fmac_f32_e32 v11, v139, v139
	v_fmac_f32_e32 v11, v140, v140
	v_fmac_f32_e32 v11, v141, v141
	v_fmac_f32_e32 v11, v142, v142
	v_fmac_f32_e32 v11, v143, v143
	v_fmac_f32_e32 v11, v144, v144
	v_fmac_f32_e32 v11, v145, v145
	v_fmac_f32_e32 v11, v146, v146
	v_fmac_f32_e32 v11, v147, v147
	ds_bpermute_b32 v12, v3, v11
	s_waitcnt lgkmcnt(0)
	v_add_f32_e32 v11, v11, v12
	ds_bpermute_b32 v12, v4, v11
	s_waitcnt lgkmcnt(0)
	v_add_f32_e32 v11, v11, v12
	ds_bpermute_b32 v12, v5, v11
	s_waitcnt lgkmcnt(0)
	v_add_f32_e32 v11, v11, v12
	ds_bpermute_b32 v12, v6, v11
	s_waitcnt lgkmcnt(0)
	v_add_f32_e32 v11, v11, v12
	ds_bpermute_b32 v12, v7, v11
	s_waitcnt lgkmcnt(0)
	v_add_f32_e32 v11, v11, v12
	ds_bpermute_b32 v12, v8, v11
	s_waitcnt lgkmcnt(0)
	v_add_f32_e32 v11, v11, v12
	v_fmamk_f32 v11, v11, 0x3a000000, v9
	v_mul_f32_e32 v13, 0x4f800000, v11
	v_cmp_gt_f32_e32 vcc, 0xf800000, v11
	s_nop 1
	v_cndmask_b32_e32 v11, v11, v13, vcc
	v_sqrt_f32_e32 v13, v11
	s_nop 0
	v_add_u32_e32 v14, -1, v13
	v_add_u32_e32 v15, 1, v13
	v_fma_f32 v16, -v14, v13, v11
	v_fma_f32 v17, -v15, v13, v11
	v_cmp_ge_f32_e64 s[0:1], 0, v16
	s_nop 1
	v_cndmask_b32_e64 v13, v13, v14, s[0:1]
	v_cmp_lt_f32_e64 s[0:1], 0, v17
	s_nop 1
	v_cndmask_b32_e64 v13, v13, v15, s[0:1]
	v_mul_f32_e32 v14, 0x37800000, v13
	v_cndmask_b32_e32 v13, v13, v14, vcc
	v_cmp_class_f32_e32 vcc, v11, v10
	s_nop 1
	v_cndmask_b32_e32 v11, v13, v11, vcc
	v_div_scale_f32 v13, s[0:1], v11, v11, 1.0
	v_rcp_f32_e32 v15, v13
	v_div_scale_f32 v14, vcc, 1.0, v11, 1.0
	v_fma_f32 v16, -v13, v15, 1.0
	v_fmac_f32_e32 v15, v16, v15
	v_mul_f32_e32 v16, v14, v15
	v_fma_f32 v17, -v13, v16, v14
	v_fmac_f32_e32 v16, v17, v15
	v_fma_f32 v13, -v13, v16, v14
	v_div_fmas_f32 v13, v13, v15, v16
	v_div_fixup_f32 v11, v13, v11, 1.0
	s_lshl_b32 s35, s5, 12
	s_add_u32 s62, s66, s35
	s_addc_u32 s63, s67, 0
	v_mul_f32_e32 v116, v116, v11
	v_mul_f32_e32 v116, v20, v116
	v_fma_f32 v116, v84, v116, v52
	v_mul_f32_e32 v117, v117, v11
	v_mul_f32_e32 v117, v21, v117
	v_fma_f32 v117, v85, v117, v53
	v_mul_f32_e32 v118, v118, v11
	v_mul_f32_e32 v118, v22, v118
	v_fma_f32 v118, v86, v118, v54
	v_mul_f32_e32 v119, v119, v11
	v_mul_f32_e32 v119, v23, v119
	v_fma_f32 v119, v87, v119, v55
	v_mul_f32_e32 v120, v120, v11
	v_mul_f32_e32 v120, v24, v120
	v_fma_f32 v120, v88, v120, v56
	v_mul_f32_e32 v121, v121, v11
	v_mul_f32_e32 v121, v25, v121
	v_fma_f32 v121, v89, v121, v57
	v_mul_f32_e32 v122, v122, v11
	v_mul_f32_e32 v122, v26, v122
	v_fma_f32 v122, v90, v122, v58
	v_mul_f32_e32 v123, v123, v11
	v_mul_f32_e32 v123, v27, v123
	v_fma_f32 v123, v91, v123, v59
	v_cvt_pk_bf16_f32 v180, v116, v117
	v_cvt_pk_bf16_f32 v181, v118, v119
	v_cvt_pk_bf16_f32 v182, v120, v121
	v_cvt_pk_bf16_f32 v183, v122, v123
	global_store_dwordx4 v2, v[180:183], s[62:63] offset:0 sc1
	v_mul_f32_e32 v124, v124, v11
	v_mul_f32_e32 v124, v28, v124
	v_fma_f32 v124, v92, v124, v60
	v_mul_f32_e32 v125, v125, v11
	v_mul_f32_e32 v125, v29, v125
	v_fma_f32 v125, v93, v125, v61
	v_mul_f32_e32 v126, v126, v11
	v_mul_f32_e32 v126, v30, v126
	v_fma_f32 v126, v94, v126, v62
	v_mul_f32_e32 v127, v127, v11
	v_mul_f32_e32 v127, v31, v127
	v_fma_f32 v127, v95, v127, v63
	v_mul_f32_e32 v128, v128, v11
	v_mul_f32_e32 v128, v32, v128
	v_fma_f32 v128, v96, v128, v64
	v_mul_f32_e32 v129, v129, v11
	v_mul_f32_e32 v129, v33, v129
	v_fma_f32 v129, v97, v129, v65
	v_mul_f32_e32 v130, v130, v11
	v_mul_f32_e32 v130, v34, v130
	v_fma_f32 v130, v98, v130, v66
	v_mul_f32_e32 v131, v131, v11
	v_mul_f32_e32 v131, v35, v131
	v_fma_f32 v131, v99, v131, v67
	v_cvt_pk_bf16_f32 v184, v124, v125
	v_cvt_pk_bf16_f32 v185, v126, v127
	v_cvt_pk_bf16_f32 v186, v128, v129
	v_cvt_pk_bf16_f32 v187, v130, v131
	global_store_dwordx4 v2, v[184:187], s[62:63] offset:1024 sc1
	v_mul_f32_e32 v132, v132, v11
	v_mul_f32_e32 v132, v36, v132
	v_fma_f32 v132, v100, v132, v68
	v_mul_f32_e32 v133, v133, v11
	v_mul_f32_e32 v133, v37, v133
	v_fma_f32 v133, v101, v133, v69
	v_mul_f32_e32 v134, v134, v11
	v_mul_f32_e32 v134, v38, v134
	v_fma_f32 v134, v102, v134, v70
	v_mul_f32_e32 v135, v135, v11
	v_mul_f32_e32 v135, v39, v135
	v_fma_f32 v135, v103, v135, v71
	v_mul_f32_e32 v136, v136, v11
	v_mul_f32_e32 v136, v40, v136
	v_fma_f32 v136, v104, v136, v72
	v_mul_f32_e32 v137, v137, v11
	v_mul_f32_e32 v137, v41, v137
	v_fma_f32 v137, v105, v137, v73
	v_mul_f32_e32 v138, v138, v11
	v_mul_f32_e32 v138, v42, v138
	v_fma_f32 v138, v106, v138, v74
	v_mul_f32_e32 v139, v139, v11
	v_mul_f32_e32 v139, v43, v139
	v_fma_f32 v139, v107, v139, v75
	v_cvt_pk_bf16_f32 v188, v132, v133
	v_cvt_pk_bf16_f32 v189, v134, v135
	v_cvt_pk_bf16_f32 v190, v136, v137
	v_cvt_pk_bf16_f32 v191, v138, v139
	global_store_dwordx4 v2, v[188:191], s[62:63] offset:2048 sc1
	v_mul_f32_e32 v140, v140, v11
	v_mul_f32_e32 v140, v44, v140
	v_fma_f32 v140, v108, v140, v76
	v_mul_f32_e32 v141, v141, v11
	v_mul_f32_e32 v141, v45, v141
	v_fma_f32 v141, v109, v141, v77
	v_mul_f32_e32 v142, v142, v11
	v_mul_f32_e32 v142, v46, v142
	v_fma_f32 v142, v110, v142, v78
	v_mul_f32_e32 v143, v143, v11
	v_mul_f32_e32 v143, v47, v143
	v_fma_f32 v143, v111, v143, v79
	v_mul_f32_e32 v144, v144, v11
	v_mul_f32_e32 v144, v48, v144
	v_fma_f32 v144, v112, v144, v80
	v_mul_f32_e32 v145, v145, v11
	v_mul_f32_e32 v145, v49, v145
	v_fma_f32 v145, v113, v145, v81
	v_mul_f32_e32 v146, v146, v11
	v_mul_f32_e32 v146, v50, v146
	v_fma_f32 v146, v114, v146, v82
	v_mul_f32_e32 v147, v147, v11
	v_mul_f32_e32 v147, v51, v147
	v_fma_f32 v147, v115, v147, v83
	v_cvt_pk_bf16_f32 v192, v140, v141
	v_cvt_pk_bf16_f32 v193, v142, v143
	v_cvt_pk_bf16_f32 v194, v144, v145
	v_cvt_pk_bf16_f32 v195, v146, v147
	global_store_dwordx4 v2, v[192:195], s[62:63] offset:3072 sc1
	s_branch .Lnr1_done

.Lnr1_1_1_same:
	s_waitcnt vmcnt(4)
	v_mul_f32_e32 v11, v148, v148
	v_fmac_f32_e32 v11, v149, v149
	v_fmac_f32_e32 v11, v150, v150
	v_fmac_f32_e32 v11, v151, v151
	v_fmac_f32_e32 v11, v152, v152
	v_fmac_f32_e32 v11, v153, v153
	v_fmac_f32_e32 v11, v154, v154
	v_fmac_f32_e32 v11, v155, v155
	v_fmac_f32_e32 v11, v156, v156
	v_fmac_f32_e32 v11, v157, v157
	v_fmac_f32_e32 v11, v158, v158
	v_fmac_f32_e32 v11, v159, v159
	v_fmac_f32_e32 v11, v160, v160
	v_fmac_f32_e32 v11, v161, v161
	v_fmac_f32_e32 v11, v162, v162
	v_fmac_f32_e32 v11, v163, v163
	v_fmac_f32_e32 v11, v164, v164
	v_fmac_f32_e32 v11, v165, v165
	v_fmac_f32_e32 v11, v166, v166
	v_fmac_f32_e32 v11, v167, v167
	v_fmac_f32_e32 v11, v168, v168
	v_fmac_f32_e32 v11, v169, v169
	v_fmac_f32_e32 v11, v170, v170
	v_fmac_f32_e32 v11, v171, v171
	v_fmac_f32_e32 v11, v172, v172
	v_fmac_f32_e32 v11, v173, v173
	v_fmac_f32_e32 v11, v174, v174
	v_fmac_f32_e32 v11, v175, v175
	v_fmac_f32_e32 v11, v176, v176
	v_fmac_f32_e32 v11, v177, v177
	v_fmac_f32_e32 v11, v178, v178
	v_fmac_f32_e32 v11, v179, v179
	ds_bpermute_b32 v12, v3, v11
	s_waitcnt lgkmcnt(0)
	v_add_f32_e32 v11, v11, v12
	ds_bpermute_b32 v12, v4, v11
	s_waitcnt lgkmcnt(0)
	v_add_f32_e32 v11, v11, v12
	ds_bpermute_b32 v12, v5, v11
	s_waitcnt lgkmcnt(0)
	v_add_f32_e32 v11, v11, v12
	ds_bpermute_b32 v12, v6, v11
	s_waitcnt lgkmcnt(0)
	v_add_f32_e32 v11, v11, v12
	ds_bpermute_b32 v12, v7, v11
	s_waitcnt lgkmcnt(0)
	v_add_f32_e32 v11, v11, v12
	ds_bpermute_b32 v12, v8, v11
	s_waitcnt lgkmcnt(0)
	v_add_f32_e32 v11, v11, v12
	v_fmamk_f32 v11, v11, 0x3a000000, v9
	v_mul_f32_e32 v13, 0x4f800000, v11
	v_cmp_gt_f32_e32 vcc, 0xf800000, v11
	s_nop 1
	v_cndmask_b32_e32 v11, v11, v13, vcc
	v_sqrt_f32_e32 v13, v11
	s_nop 0
	v_add_u32_e32 v14, -1, v13
	v_add_u32_e32 v15, 1, v13
	v_fma_f32 v16, -v14, v13, v11
	v_fma_f32 v17, -v15, v13, v11
	v_cmp_ge_f32_e64 s[0:1], 0, v16
	s_nop 1
	v_cndmask_b32_e64 v13, v13, v14, s[0:1]
	v_cmp_lt_f32_e64 s[0:1], 0, v17
	s_nop 1
	v_cndmask_b32_e64 v13, v13, v15, s[0:1]
	v_mul_f32_e32 v14, 0x37800000, v13
	v_cndmask_b32_e32 v13, v13, v14, vcc
	v_cmp_class_f32_e32 vcc, v11, v10
	s_nop 1
	v_cndmask_b32_e32 v11, v13, v11, vcc
	v_div_scale_f32 v13, s[0:1], v11, v11, 1.0
	v_rcp_f32_e32 v15, v13
	v_div_scale_f32 v14, vcc, 1.0, v11, 1.0
	v_fma_f32 v16, -v13, v15, 1.0
	v_fmac_f32_e32 v15, v16, v15
	v_mul_f32_e32 v16, v14, v15
	v_fma_f32 v17, -v13, v16, v14
	v_fmac_f32_e32 v16, v17, v15
	v_fma_f32 v13, -v13, v16, v14
	v_div_fmas_f32 v13, v13, v15, v16
	v_div_fixup_f32 v11, v13, v11, 1.0
	s_lshl_b32 s35, s5, 12
	s_add_u32 s62, s66, s35
	s_addc_u32 s63, s67, 0
	v_mul_f32_e32 v148, v148, v11
	v_mul_f32_e32 v148, v20, v148
	v_fma_f32 v148, v84, v148, v52
	v_mul_f32_e32 v149, v149, v11
	v_mul_f32_e32 v149, v21, v149
	v_fma_f32 v149, v85, v149, v53
	v_mul_f32_e32 v150, v150, v11
	v_mul_f32_e32 v150, v22, v150
	v_fma_f32 v150, v86, v150, v54
	v_mul_f32_e32 v151, v151, v11
	v_mul_f32_e32 v151, v23, v151
	v_fma_f32 v151, v87, v151, v55
	v_mul_f32_e32 v152, v152, v11
	v_mul_f32_e32 v152, v24, v152
	v_fma_f32 v152, v88, v152, v56
	v_mul_f32_e32 v153, v153, v11
	v_mul_f32_e32 v153, v25, v153
	v_fma_f32 v153, v89, v153, v57
	v_mul_f32_e32 v154, v154, v11
	v_mul_f32_e32 v154, v26, v154
	v_fma_f32 v154, v90, v154, v58
	v_mul_f32_e32 v155, v155, v11
	v_mul_f32_e32 v155, v27, v155
	v_fma_f32 v155, v91, v155, v59
	v_cvt_pk_bf16_f32 v180, v148, v149
	v_cvt_pk_bf16_f32 v181, v150, v151
	v_cvt_pk_bf16_f32 v182, v152, v153
	v_cvt_pk_bf16_f32 v183, v154, v155
	global_store_dwordx4 v2, v[180:183], s[62:63] offset:0 sc1
	v_mul_f32_e32 v156, v156, v11
	v_mul_f32_e32 v156, v28, v156
	v_fma_f32 v156, v92, v156, v60
	v_mul_f32_e32 v157, v157, v11
	v_mul_f32_e32 v157, v29, v157
	v_fma_f32 v157, v93, v157, v61
	v_mul_f32_e32 v158, v158, v11
	v_mul_f32_e32 v158, v30, v158
	v_fma_f32 v158, v94, v158, v62
	v_mul_f32_e32 v159, v159, v11
	v_mul_f32_e32 v159, v31, v159
	v_fma_f32 v159, v95, v159, v63
	v_mul_f32_e32 v160, v160, v11
	v_mul_f32_e32 v160, v32, v160
	v_fma_f32 v160, v96, v160, v64
	v_mul_f32_e32 v161, v161, v11
	v_mul_f32_e32 v161, v33, v161
	v_fma_f32 v161, v97, v161, v65
	v_mul_f32_e32 v162, v162, v11
	v_mul_f32_e32 v162, v34, v162
	v_fma_f32 v162, v98, v162, v66
	v_mul_f32_e32 v163, v163, v11
	v_mul_f32_e32 v163, v35, v163
	v_fma_f32 v163, v99, v163, v67
	v_cvt_pk_bf16_f32 v184, v156, v157
	v_cvt_pk_bf16_f32 v185, v158, v159
	v_cvt_pk_bf16_f32 v186, v160, v161
	v_cvt_pk_bf16_f32 v187, v162, v163
	global_store_dwordx4 v2, v[184:187], s[62:63] offset:1024 sc1
	v_mul_f32_e32 v164, v164, v11
	v_mul_f32_e32 v164, v36, v164
	v_fma_f32 v164, v100, v164, v68
	v_mul_f32_e32 v165, v165, v11
	v_mul_f32_e32 v165, v37, v165
	v_fma_f32 v165, v101, v165, v69
	v_mul_f32_e32 v166, v166, v11
	v_mul_f32_e32 v166, v38, v166
	v_fma_f32 v166, v102, v166, v70
	v_mul_f32_e32 v167, v167, v11
	v_mul_f32_e32 v167, v39, v167
	v_fma_f32 v167, v103, v167, v71
	v_mul_f32_e32 v168, v168, v11
	v_mul_f32_e32 v168, v40, v168
	v_fma_f32 v168, v104, v168, v72
	v_mul_f32_e32 v169, v169, v11
	v_mul_f32_e32 v169, v41, v169
	v_fma_f32 v169, v105, v169, v73
	v_mul_f32_e32 v170, v170, v11
	v_mul_f32_e32 v170, v42, v170
	v_fma_f32 v170, v106, v170, v74
	v_mul_f32_e32 v171, v171, v11
	v_mul_f32_e32 v171, v43, v171
	v_fma_f32 v171, v107, v171, v75
	v_cvt_pk_bf16_f32 v188, v164, v165
	v_cvt_pk_bf16_f32 v189, v166, v167
	v_cvt_pk_bf16_f32 v190, v168, v169
	v_cvt_pk_bf16_f32 v191, v170, v171
	global_store_dwordx4 v2, v[188:191], s[62:63] offset:2048 sc1
	v_mul_f32_e32 v172, v172, v11
	v_mul_f32_e32 v172, v44, v172
	v_fma_f32 v172, v108, v172, v76
	v_mul_f32_e32 v173, v173, v11
	v_mul_f32_e32 v173, v45, v173
	v_fma_f32 v173, v109, v173, v77
	v_mul_f32_e32 v174, v174, v11
	v_mul_f32_e32 v174, v46, v174
	v_fma_f32 v174, v110, v174, v78
	v_mul_f32_e32 v175, v175, v11
	v_mul_f32_e32 v175, v47, v175
	v_fma_f32 v175, v111, v175, v79
	v_mul_f32_e32 v176, v176, v11
	v_mul_f32_e32 v176, v48, v176
	v_fma_f32 v176, v112, v176, v80
	v_mul_f32_e32 v177, v177, v11
	v_mul_f32_e32 v177, v49, v177
	v_fma_f32 v177, v113, v177, v81
	v_mul_f32_e32 v178, v178, v11
	v_mul_f32_e32 v178, v50, v178
	v_fma_f32 v178, v114, v178, v82
	v_mul_f32_e32 v179, v179, v11
	v_mul_f32_e32 v179, v51, v179
	v_fma_f32 v179, v115, v179, v83
	v_cvt_pk_bf16_f32 v192, v172, v173
	v_cvt_pk_bf16_f32 v193, v174, v175
	v_cvt_pk_bf16_f32 v194, v176, v177
	v_cvt_pk_bf16_f32 v195, v178, v179
	global_store_dwordx4 v2, v[192:195], s[62:63] offset:3072 sc1
	s_branch .Lnr1_done

.Lnr1_orig:
	s_lshl_b32 s0, s96, 3
	s_add_i32 s2, s93, s0
	s_cmpk_gt_i32 s2, 0x23ff
	s_cbranch_scc1 .LBB0_219
	s_waitcnt vmcnt(11)
	v_mbcnt_hi_u32_b32 v1, -1, v212
	v_and_b32_e32 v2, 0xffffffc0, v1
	v_add_u32_e32 v2, 64, v2
	v_xor_b32_e32 v3, 1, v1
	v_cmp_lt_i32_e32 vcc, v3, v2
	v_lshlrev_b32_e32 v0, 2, v1
	v_and_b32_e32 v0, 0xfc, v0
	v_cndmask_b32_e32 v3, v1, v3, vcc
	v_lshlrev_b32_e32 v46, 2, v3
	v_xor_b32_e32 v3, 2, v1
	v_cmp_lt_i32_e32 vcc, v3, v2
	s_waitcnt vmcnt(10)
	v_and_b32_e32 v5, 1, v1
	v_readlane_b32 s36, v244, 3
	v_cndmask_b32_e32 v3, v1, v3, vcc
	v_lshlrev_b32_e32 v47, 2, v3
	v_xor_b32_e32 v3, 4, v1
	v_cmp_lt_i32_e32 vcc, v3, v2
	v_mov_b32_e32 v33, 0
	v_or_b32_e32 v4, 0x600, v0
	v_cndmask_b32_e32 v3, v1, v3, vcc
	v_lshlrev_b32_e32 v48, 2, v3
	v_xor_b32_e32 v3, 8, v1
	v_cmp_lt_i32_e32 vcc, v3, v2
	v_readlane_b32 s48, v244, 15
	v_readlane_b32 s49, v244, 16
	v_cndmask_b32_e32 v3, v1, v3, vcc
	v_lshlrev_b32_e32 v49, 2, v3
	v_xor_b32_e32 v3, 16, v1
	v_cmp_lt_i32_e32 vcc, v3, v2
	v_readlane_b32 s50, v244, 17
	v_readlane_b32 s51, v244, 18
	v_cndmask_b32_e32 v3, v1, v3, vcc
	v_lshlrev_b32_e32 v50, 2, v3
	v_xor_b32_e32 v3, 32, v1
	v_cmp_lt_i32_e32 vcc, v3, v2
	s_mov_b64 s[16:17], s[48:49]
	s_waitcnt vmcnt(8)
	v_or_b32_e32 v12, 0x400, v0
	v_cndmask_b32_e32 v2, v1, v3, vcc
	v_lshlrev_b32_e32 v1, 3, v1
	v_and_b32_e32 v32, 0x1f0, v1
	v_lshlrev_b32_e32 v51, 2, v2
	v_lshl_add_u64 v[2:3], s[76:77], 0, v[32:33]
	v_lshlrev_b32_e32 v32, 2, v4
	v_lshl_add_u64 v[34:35], s[16:17], 0, v[32:33]
	v_lshlrev_b32_e32 v32, 2, v0
	v_lshl_add_u64 v[36:37], s[16:17], 0, v[32:33]
	v_lshlrev_b32_e32 v32, 2, v12
	v_or_b32_e32 v14, 0x500, v0
	v_lshl_add_u64 v[38:39], s[16:17], 0, v[32:33]
	v_lshlrev_b32_e32 v32, 2, v14
	s_waitcnt vmcnt(7)
	v_or_b32_e32 v16, 0x700, v0
	v_lshl_add_u64 v[40:41], s[16:17], 0, v[32:33]
	v_lshlrev_b32_e32 v32, 2, v16
	v_lshl_add_u64 v[42:43], s[16:17], 0, v[32:33]
	v_lshlrev_b32_e32 v32, 9, v5
	s_add_u32 s22, s76, 0xe000
	v_or_b32_e32 v6, 0x100, v0
	v_or_b32_e32 v8, 0x200, v0
	v_or_b32_e32 v10, 0x300, v0
	v_lshl_add_u64 v[2:3], v[2:3], 0, v[32:33]
	s_mov_b64 s[4:5], 0x11189000
	s_addc_u32 s23, s77, 0
	s_lshl_b32 s24, s87, 3
	s_mov_b32 s7, 0
	v_cmp_eq_u32_e64 s[0:1], 0, v5
	v_lshl_add_u64 v[44:45], v[2:3], 0, s[4:5]
	v_lshlrev_b32_e32 v32, 2, v0
	s_movk_i32 s25, 0x1000
	v_mov_b32_e32 v52, 0x358637bd
	s_mov_b32 s26, 0xf800000
	v_mov_b32_e32 v53, 0x260
	v_lshlrev_b32_e32 v54, 2, v6
	v_lshlrev_b32_e32 v55, 2, v8
	v_lshlrev_b32_e32 v56, 2, v10
	s_mov_b64 s[8:9], 0x400
	v_lshlrev_b32_e32 v57, 2, v12
	v_lshlrev_b32_e32 v58, 2, v14
	s_mov_b64 s[10:11], 0x800
	v_lshlrev_b32_e32 v59, 2, v4
	v_lshlrev_b32_e32 v60, 2, v16
	s_mov_b64 s[12:13], 0xc00
	v_readlane_b32 s37, v244, 4
	v_readlane_b32 s38, v244, 5
	v_readlane_b32 s39, v244, 6
	v_readlane_b32 s40, v244, 7
	v_readlane_b32 s41, v244, 8
	v_readlane_b32 s42, v244, 9
	v_readlane_b32 s43, v244, 10
	v_readlane_b32 s44, v244, 11
	v_readlane_b32 s45, v244, 12
	v_readlane_b32 s46, v244, 13
	v_readlane_b32 s47, v244, 14
	s_mov_b64 s[18:19], s[50:51]
	s_branch .LBB0_215

.LBB0_755:
	s_cmp_lt_i32 s78, 7
	s_cselect_b64 s[0:1], -1, 0
	s_cmp_gt_i32 s79, 6
	s_cselect_b64 s[2:3], -1, 0
	s_and_b64 s[0:1], s[0:1], s[2:3]
	s_andn2_b64 vcc, exec, s[0:1]
	s_cbranch_vccnz .LBB0_816
	s_cmp_lg_u32 s87, 0x100
	s_cbranch_scc1 .Lnr6_orig
	v_mbcnt_hi_u32_b32 v0, -1, v212
	v_and_b32_e32 v0, 63, v0
	v_lshlrev_b32_e32 v1, 5, v0
	v_lshlrev_b32_e32 v2, 4, v0
	v_mov_b32_e32 v9, 0x358637bd
	v_mov_b32_e32 v10, 0x260
	v_xor_b32_e32 v3, 1, v0
	v_lshlrev_b32_e32 v3, 2, v3
	v_xor_b32_e32 v4, 2, v0
	v_lshlrev_b32_e32 v4, 2, v4
	v_xor_b32_e32 v5, 4, v0
	v_lshlrev_b32_e32 v5, 2, v5
	v_xor_b32_e32 v6, 8, v0
	v_lshlrev_b32_e32 v6, 2, v6
	v_xor_b32_e32 v7, 16, v0
	v_lshlrev_b32_e32 v7, 2, v7
	v_xor_b32_e32 v8, 32, v0
	v_lshlrev_b32_e32 v8, 2, v8
	s_lshl_b32 s31, s96, 3
	s_add_u32 s31, s31, s93
	s_add_u32 s64, s76, 0xc989000
	s_addc_u32 s65, s77, 0
	s_add_u32 s66, s76, 0x11189000
	s_addc_u32 s67, s77, 0
	s_add_u32 s68, s76, 0x14000
	s_addc_u32 s69, s77, 0
	v_readlane_b32 s54, v244, 17
	v_readlane_b32 s55, v244, 18
	s_mov_b32 s23, -1
	s_mul_i32 s5, s31, 9
	s_lshr_b32 s5, s5, 1
	s_add_u32 s41, s31, 1
	s_mul_i32 s41, s41, 9
	s_lshr_b32 s41, s41, 1
	s_nop 0
	s_add_u32 s54, s54, 0x0
	s_addc_u32 s55, s55, 0
	s_add_u32 s56, s54, 0x1000
	s_addc_u32 s57, s55, 0
	s_cmp_ge_u32 s5, s41
	s_cbranch_scc1 .Lnr6_done
	global_load_dwordx4 v[20:23], v1, s[54:55] offset:0
	global_load_dwordx4 v[24:27], v1, s[54:55] offset:16
	global_load_dwordx4 v[28:31], v1, s[54:55] offset:2048
	global_load_dwordx4 v[32:35], v1, s[54:55] offset:2064
	global_load_dwordx4 v[36:39], v1, s[56:57] offset:0
	global_load_dwordx4 v[40:43], v1, s[56:57] offset:16
	global_load_dwordx4 v[44:47], v1, s[56:57] offset:2048
	global_load_dwordx4 v[48:51], v1, s[56:57] offset:2064
	s_lshl_b32 s35, s5, 13
	s_add_u32 s2, s64, s35
	s_addc_u32 s3, s65, 0
	s_add_u32 s6, s2, 0x1000
	s_addc_u32 s7, s3, 0
	global_load_dwordx4 v[116:119], v1, s[2:3] offset:0
	global_load_dwordx4 v[120:123], v1, s[2:3] offset:16
	global_load_dwordx4 v[124:127], v1, s[2:3] offset:2048
	global_load_dwordx4 v[128:131], v1, s[2:3] offset:2064
	global_load_dwordx4 v[132:135], v1, s[6:7] offset:0
	global_load_dwordx4 v[136:139], v1, s[6:7] offset:16
	global_load_dwordx4 v[140:143], v1, s[6:7] offset:2048
	global_load_dwordx4 v[144:147], v1, s[6:7] offset:2064
	s_waitcnt vmcnt(8)
.Lnr6_loop:
	s_add_u32 s31, s5, 1
	s_cmp_ge_u32 s31, s41
	s_cbranch_scc1 .Lnr6_last0
	s_lshl_b32 s35, s31, 13
	s_add_u32 s10, s64, s35
	s_addc_u32 s11, s65, 0
	s_add_u32 s32, s10, 0x1000
	s_addc_u32 s33, s11, 0
	global_load_dwordx4 v[148:151], v1, s[10:11] offset:0
	global_load_dwordx4 v[152:155], v1, s[10:11] offset:16
	global_load_dwordx4 v[156:159], v1, s[10:11] offset:2048
	global_load_dwordx4 v[160:163], v1, s[10:11] offset:2064
	global_load_dwordx4 v[164:167], v1, s[32:33] offset:0
	global_load_dwordx4 v[168:171], v1, s[32:33] offset:16
	global_load_dwordx4 v[172:175], v1, s[32:33] offset:2048
	global_load_dwordx4 v[176:179], v1, s[32:33] offset:2064
	s_cmp_ge_u32 s5, 0x900
	s_cselect_b32 s25, 1, 0
	s_cmp_ge_u32 s5, 0x1200
	s_cselect_b32 s35, 1, 0
	s_add_u32 s25, s25, s35
	s_cmp_ge_u32 s5, 0x1b00
	s_cselect_b32 s35, 1, 0
	s_add_u32 s25, s25, s35
	s_mul_i32 s27, s25, 0x900
	s_sub_u32 s27, s5, s27
	s_cmp_lt_u32 s27, 0x100
	s_cselect_b32 s20, 4, s25
	s_cmp_eq_u32 s20, s23
	s_cbranch_scc1 .Lnr6_0_0_same
	s_mov_b32 s23, s20
	s_mul_i32 s35, s20, 0xc000
	s_add_u32 s42, s68, s35
	s_addc_u32 s43, s69, 0
	s_add_u32 s44, s42, 0x1000
	s_addc_u32 s45, s43, 0
	global_load_dwordx4 v[52:55], v1, s[42:43] offset:0
	global_load_dwordx4 v[56:59], v1, s[42:43] offset:16
	global_load_dwordx4 v[60:63], v1, s[42:43] offset:2048
	global_load_dwordx4 v[64:67], v1, s[42:43] offset:2064
	global_load_dwordx4 v[68:71], v1, s[44:45] offset:0
	global_load_dwordx4 v[72:75], v1, s[44:45] offset:16
	global_load_dwordx4 v[76:79], v1, s[44:45] offset:2048
	global_load_dwordx4 v[80:83], v1, s[44:45] offset:2064
	s_add_u32 s42, s42, 0x2000
	s_addc_u32 s43, s43, 0
	s_add_u32 s44, s44, 0x2000
	s_addc_u32 s45, s45, 0
	global_load_dwordx4 v[84:87], v1, s[42:43] offset:0
	global_load_dwordx4 v[88:91], v1, s[42:43] offset:16
	global_load_dwordx4 v[92:95], v1, s[42:43] offset:2048
	global_load_dwordx4 v[96:99], v1, s[42:43] offset:2064
	global_load_dwordx4 v[100:103], v1, s[44:45] offset:0
	global_load_dwordx4 v[104:107], v1, s[44:45] offset:16
	global_load_dwordx4 v[108:111], v1, s[44:45] offset:2048
	global_load_dwordx4 v[112:115], v1, s[44:45] offset:2064
	s_waitcnt vmcnt(0)
	v_add_f32_e32 v84, 1.0, v84
	v_add_f32_e32 v85, 1.0, v85
	v_add_f32_e32 v86, 1.0, v86
	v_add_f32_e32 v87, 1.0, v87
	v_add_f32_e32 v88, 1.0, v88
	v_add_f32_e32 v89, 1.0, v89
	v_add_f32_e32 v90, 1.0, v90
	v_add_f32_e32 v91, 1.0, v91
	v_add_f32_e32 v92, 1.0, v92
	v_add_f32_e32 v93, 1.0, v93
	v_add_f32_e32 v94, 1.0, v94
	v_add_f32_e32 v95, 1.0, v95
	v_add_f32_e32 v96, 1.0, v96
	v_add_f32_e32 v97, 1.0, v97
	v_add_f32_e32 v98, 1.0, v98
	v_add_f32_e32 v99, 1.0, v99
	v_add_f32_e32 v100, 1.0, v100
	v_add_f32_e32 v101, 1.0, v101
	v_add_f32_e32 v102, 1.0, v102
	v_add_f32_e32 v103, 1.0, v103
	v_add_f32_e32 v104, 1.0, v104
	v_add_f32_e32 v105, 1.0, v105
	v_add_f32_e32 v106, 1.0, v106
	v_add_f32_e32 v107, 1.0, v107
	v_add_f32_e32 v108, 1.0, v108
	v_add_f32_e32 v109, 1.0, v109
	v_add_f32_e32 v110, 1.0, v110
	v_add_f32_e32 v111, 1.0, v111
	v_add_f32_e32 v112, 1.0, v112
	v_add_f32_e32 v113, 1.0, v113
	v_add_f32_e32 v114, 1.0, v114
	v_add_f32_e32 v115, 1.0, v115
.Lnr6_0_0_same:
	s_waitcnt vmcnt(12)
	v_mul_f32_e32 v11, v116, v116
	v_fmac_f32_e32 v11, v117, v117
	v_fmac_f32_e32 v11, v118, v118
	v_fmac_f32_e32 v11, v119, v119
	v_fmac_f32_e32 v11, v120, v120
	v_fmac_f32_e32 v11, v121, v121
	v_fmac_f32_e32 v11, v122, v122
	v_fmac_f32_e32 v11, v123, v123
	v_fmac_f32_e32 v11, v124, v124
	v_fmac_f32_e32 v11, v125, v125
	v_fmac_f32_e32 v11, v126, v126
	v_fmac_f32_e32 v11, v127, v127
	v_fmac_f32_e32 v11, v128, v128
	v_fmac_f32_e32 v11, v129, v129
	v_fmac_f32_e32 v11, v130, v130
	v_fmac_f32_e32 v11, v131, v131
	v_fmac_f32_e32 v11, v132, v132
	v_fmac_f32_e32 v11, v133, v133
	v_fmac_f32_e32 v11, v134, v134
	v_fmac_f32_e32 v11, v135, v135
	v_fmac_f32_e32 v11, v136, v136
	v_fmac_f32_e32 v11, v137, v137
	v_fmac_f32_e32 v11, v138, v138
	v_fmac_f32_e32 v11, v139, v139
	v_fmac_f32_e32 v11, v140, v140
	v_fmac_f32_e32 v11, v141, v141
	v_fmac_f32_e32 v11, v142, v142
	v_fmac_f32_e32 v11, v143, v143
	v_fmac_f32_e32 v11, v144, v144
	v_fmac_f32_e32 v11, v145, v145
	v_fmac_f32_e32 v11, v146, v146
	v_fmac_f32_e32 v11, v147, v147
	ds_bpermute_b32 v12, v3, v11
	s_waitcnt lgkmcnt(0)
	v_add_f32_e32 v11, v11, v12
	ds_bpermute_b32 v12, v4, v11
	s_waitcnt lgkmcnt(0)
	v_add_f32_e32 v11, v11, v12
	ds_bpermute_b32 v12, v5, v11
	s_waitcnt lgkmcnt(0)
	v_add_f32_e32 v11, v11, v12
	ds_bpermute_b32 v12, v6, v11
	s_waitcnt lgkmcnt(0)
	v_add_f32_e32 v11, v11, v12
	ds_bpermute_b32 v12, v7, v11
	s_waitcnt lgkmcnt(0)
	v_add_f32_e32 v11, v11, v12
	ds_bpermute_b32 v12, v8, v11
	s_waitcnt lgkmcnt(0)
	v_add_f32_e32 v11, v11, v12
	v_fmamk_f32 v11, v11, 0x3a000000, v9
	v_mul_f32_e32 v13, 0x4f800000, v11
	v_cmp_gt_f32_e32 vcc, 0xf800000, v11
	s_nop 1
	v_cndmask_b32_e32 v11, v11, v13, vcc
	v_sqrt_f32_e32 v13, v11
	s_nop 0
	v_add_u32_e32 v14, -1, v13
	v_add_u32_e32 v15, 1, v13
	v_fma_f32 v16, -v14, v13, v11
	v_fma_f32 v17, -v15, v13, v11
	v_cmp_ge_f32_e64 s[0:1], 0, v16
	s_nop 1
	v_cndmask_b32_e64 v13, v13, v14, s[0:1]
	v_cmp_lt_f32_e64 s[0:1], 0, v17
	s_nop 1
	v_cndmask_b32_e64 v13, v13, v15, s[0:1]
	v_mul_f32_e32 v14, 0x37800000, v13
	v_cndmask_b32_e32 v13, v13, v14, vcc
	v_cmp_class_f32_e32 vcc, v11, v10
	s_nop 1
	v_cndmask_b32_e32 v11, v13, v11, vcc
	v_div_scale_f32 v13, s[0:1], v11, v11, 1.0
	v_rcp_f32_e32 v15, v13
	v_div_scale_f32 v14, vcc, 1.0, v11, 1.0
	v_fma_f32 v16, -v13, v15, 1.0
	v_fmac_f32_e32 v15, v16, v15
	v_mul_f32_e32 v16, v14, v15
	v_fma_f32 v17, -v13, v16, v14
	v_fmac_f32_e32 v16, v17, v15
	v_fma_f32 v13, -v13, v16, v14
	v_div_fmas_f32 v13, v13, v15, v16
	v_div_fixup_f32 v11, v13, v11, 1.0
	s_lshl_b32 s35, s5, 12
	s_add_u32 s62, s66, s35
	s_addc_u32 s63, s67, 0
	v_mul_f32_e32 v116, v116, v11
	v_mul_f32_e32 v116, v20, v116
	v_fma_f32 v116, v84, v116, v52
	v_mul_f32_e32 v117, v117, v11
	v_mul_f32_e32 v117, v21, v117
	v_fma_f32 v117, v85, v117, v53
	v_mul_f32_e32 v118, v118, v11
	v_mul_f32_e32 v118, v22, v118
	v_fma_f32 v118, v86, v118, v54
	v_mul_f32_e32 v119, v119, v11
	v_mul_f32_e32 v119, v23, v119
	v_fma_f32 v119, v87, v119, v55
	v_mul_f32_e32 v120, v120, v11
	v_mul_f32_e32 v120, v24, v120
	v_fma_f32 v120, v88, v120, v56
	v_mul_f32_e32 v121, v121, v11
	v_mul_f32_e32 v121, v25, v121
	v_fma_f32 v121, v89, v121, v57
	v_mul_f32_e32 v122, v122, v11
	v_mul_f32_e32 v122, v26, v122
	v_fma_f32 v122, v90, v122, v58
	v_mul_f32_e32 v123, v123, v11
	v_mul_f32_e32 v123, v27, v123
	v_fma_f32 v123, v91, v123, v59
	v_cvt_pk_bf16_f32 v180, v116, v117
	v_cvt_pk_bf16_f32 v181, v118, v119
	v_cvt_pk_bf16_f32 v182, v120, v121
	v_cvt_pk_bf16_f32 v183, v122, v123
	global_store_dwordx4 v2, v[180:183], s[62:63] offset:0 sc1
	v_mul_f32_e32 v124, v124, v11
	v_mul_f32_e32 v124, v28, v124
	v_fma_f32 v124, v92, v124, v60
	v_mul_f32_e32 v125, v125, v11
	v_mul_f32_e32 v125, v29, v125
	v_fma_f32 v125, v93, v125, v61
	v_mul_f32_e32 v126, v126, v11
	v_mul_f32_e32 v126, v30, v126
	v_fma_f32 v126, v94, v126, v62
	v_mul_f32_e32 v127, v127, v11
	v_mul_f32_e32 v127, v31, v127
	v_fma_f32 v127, v95, v127, v63
	v_mul_f32_e32 v128, v128, v11
	v_mul_f32_e32 v128, v32, v128
	v_fma_f32 v128, v96, v128, v64
	v_mul_f32_e32 v129, v129, v11
	v_mul_f32_e32 v129, v33, v129
	v_fma_f32 v129, v97, v129, v65
	v_mul_f32_e32 v130, v130, v11
	v_mul_f32_e32 v130, v34, v130
	v_fma_f32 v130, v98, v130, v66
	v_mul_f32_e32 v131, v131, v11
	v_mul_f32_e32 v131, v35, v131
	v_fma_f32 v131, v99, v131, v67
	v_cvt_pk_bf16_f32 v184, v124, v125
	v_cvt_pk_bf16_f32 v185, v126, v127
	v_cvt_pk_bf16_f32 v186, v128, v129
	v_cvt_pk_bf16_f32 v187, v130, v131
	global_store_dwordx4 v2, v[184:187], s[62:63] offset:1024 sc1
	v_mul_f32_e32 v132, v132, v11
	v_mul_f32_e32 v132, v36, v132
	v_fma_f32 v132, v100, v132, v68
	v_mul_f32_e32 v133, v133, v11
	v_mul_f32_e32 v133, v37, v133
	v_fma_f32 v133, v101, v133, v69
	v_mul_f32_e32 v134, v134, v11
	v_mul_f32_e32 v134, v38, v134
	v_fma_f32 v134, v102, v134, v70
	v_mul_f32_e32 v135, v135, v11
	v_mul_f32_e32 v135, v39, v135
	v_fma_f32 v135, v103, v135, v71
	v_mul_f32_e32 v136, v136, v11
	v_mul_f32_e32 v136, v40, v136
	v_fma_f32 v136, v104, v136, v72
	v_mul_f32_e32 v137, v137, v11
	v_mul_f32_e32 v137, v41, v137
	v_fma_f32 v137, v105, v137, v73
	v_mul_f32_e32 v138, v138, v11
	v_mul_f32_e32 v138, v42, v138
	v_fma_f32 v138, v106, v138, v74
	v_mul_f32_e32 v139, v139, v11
	v_mul_f32_e32 v139, v43, v139
	v_fma_f32 v139, v107, v139, v75
	v_cvt_pk_bf16_f32 v188, v132, v133
	v_cvt_pk_bf16_f32 v189, v134, v135
	v_cvt_pk_bf16_f32 v190, v136, v137
	v_cvt_pk_bf16_f32 v191, v138, v139
	global_store_dwordx4 v2, v[188:191], s[62:63] offset:2048 sc1
	v_mul_f32_e32 v140, v140, v11
	v_mul_f32_e32 v140, v44, v140
	v_fma_f32 v140, v108, v140, v76
	v_mul_f32_e32 v141, v141, v11
	v_mul_f32_e32 v141, v45, v141
	v_fma_f32 v141, v109, v141, v77
	v_mul_f32_e32 v142, v142, v11
	v_mul_f32_e32 v142, v46, v142
	v_fma_f32 v142, v110, v142, v78
	v_mul_f32_e32 v143, v143, v11
	v_mul_f32_e32 v143, v47, v143
	v_fma_f32 v143, v111, v143, v79
	v_mul_f32_e32 v144, v144, v11
	v_mul_f32_e32 v144, v48, v144
	v_fma_f32 v144, v112, v144, v80
	v_mul_f32_e32 v145, v145, v11
	v_mul_f32_e32 v145, v49, v145
	v_fma_f32 v145, v113, v145, v81
	v_mul_f32_e32 v146, v146, v11
	v_mul_f32_e32 v146, v50, v146
	v_fma_f32 v146, v114, v146, v82
	v_mul_f32_e32 v147, v147, v11
	v_mul_f32_e32 v147, v51, v147
	v_fma_f32 v147, v115, v147, v83
	v_cvt_pk_bf16_f32 v192, v140, v141
	v_cvt_pk_bf16_f32 v193, v142, v143
	v_cvt_pk_bf16_f32 v194, v144, v145
	v_cvt_pk_bf16_f32 v195, v146, v147
	global_store_dwordx4 v2, v[192:195], s[62:63] offset:3072 sc1
	s_add_u32 s5, s5, 1
	s_add_u32 s31, s5, 1
	s_cmp_ge_u32 s31, s41
	s_cbranch_scc1 .Lnr6_last1
	s_lshl_b32 s35, s31, 13
	s_add_u32 s2, s64, s35
	s_addc_u32 s3, s65, 0
	s_add_u32 s6, s2, 0x1000
	s_addc_u32 s7, s3, 0
	global_load_dwordx4 v[116:119], v1, s[2:3] offset:0
	global_load_dwordx4 v[120:123], v1, s[2:3] offset:16
	global_load_dwordx4 v[124:127], v1, s[2:3] offset:2048
	global_load_dwordx4 v[128:131], v1, s[2:3] offset:2064
	global_load_dwordx4 v[132:135], v1, s[6:7] offset:0
	global_load_dwordx4 v[136:139], v1, s[6:7] offset:16
	global_load_dwordx4 v[140:143], v1, s[6:7] offset:2048
	global_load_dwordx4 v[144:147], v1, s[6:7] offset:2064
	s_cmp_ge_u32 s5, 0x900
	s_cselect_b32 s25, 1, 0
	s_cmp_ge_u32 s5, 0x1200
	s_cselect_b32 s35, 1, 0
	s_add_u32 s25, s25, s35
	s_cmp_ge_u32 s5, 0x1b00
	s_cselect_b32 s35, 1, 0
	s_add_u32 s25, s25, s35
	s_mul_i32 s27, s25, 0x900
	s_sub_u32 s27, s5, s27
	s_cmp_lt_u32 s27, 0x100
	s_cselect_b32 s20, 4, s25
	s_cmp_eq_u32 s20, s23
	s_cbranch_scc1 .Lnr6_1_0_same
	s_mov_b32 s23, s20
	s_mul_i32 s35, s20, 0xc000
	s_add_u32 s42, s68, s35
	s_addc_u32 s43, s69, 0
	s_add_u32 s44, s42, 0x1000
	s_addc_u32 s45, s43, 0
	global_load_dwordx4 v[52:55], v1, s[42:43] offset:0
	global_load_dwordx4 v[56:59], v1, s[42:43] offset:16
	global_load_dwordx4 v[60:63], v1, s[42:43] offset:2048
	global_load_dwordx4 v[64:67], v1, s[42:43] offset:2064
	global_load_dwordx4 v[68:71], v1, s[44:45] offset:0
	global_load_dwordx4 v[72:75], v1, s[44:45] offset:16
	global_load_dwordx4 v[76:79], v1, s[44:45] offset:2048
	global_load_dwordx4 v[80:83], v1, s[44:45] offset:2064
	s_add_u32 s42, s42, 0x2000
	s_addc_u32 s43, s43, 0
	s_add_u32 s44, s44, 0x2000
	s_addc_u32 s45, s45, 0
	global_load_dwordx4 v[84:87], v1, s[42:43] offset:0
	global_load_dwordx4 v[88:91], v1, s[42:43] offset:16
	global_load_dwordx4 v[92:95], v1, s[42:43] offset:2048
	global_load_dwordx4 v[96:99], v1, s[42:43] offset:2064
	global_load_dwordx4 v[100:103], v1, s[44:45] offset:0
	global_load_dwordx4 v[104:107], v1, s[44:45] offset:16
	global_load_dwordx4 v[108:111], v1, s[44:45] offset:2048
	global_load_dwordx4 v[112:115], v1, s[44:45] offset:2064
	s_waitcnt vmcnt(0)
	v_add_f32_e32 v84, 1.0, v84
	v_add_f32_e32 v85, 1.0, v85
	v_add_f32_e32 v86, 1.0, v86
	v_add_f32_e32 v87, 1.0, v87
	v_add_f32_e32 v88, 1.0, v88
	v_add_f32_e32 v89, 1.0, v89
	v_add_f32_e32 v90, 1.0, v90
	v_add_f32_e32 v91, 1.0, v91
	v_add_f32_e32 v92, 1.0, v92
	v_add_f32_e32 v93, 1.0, v93
	v_add_f32_e32 v94, 1.0, v94
	v_add_f32_e32 v95, 1.0, v95
	v_add_f32_e32 v96, 1.0, v96
	v_add_f32_e32 v97, 1.0, v97
	v_add_f32_e32 v98, 1.0, v98
	v_add_f32_e32 v99, 1.0, v99
	v_add_f32_e32 v100, 1.0, v100
	v_add_f32_e32 v101, 1.0, v101
	v_add_f32_e32 v102, 1.0, v102
	v_add_f32_e32 v103, 1.0, v103
	v_add_f32_e32 v104, 1.0, v104
	v_add_f32_e32 v105, 1.0, v105
	v_add_f32_e32 v106, 1.0, v106
	v_add_f32_e32 v107, 1.0, v107
	v_add_f32_e32 v108, 1.0, v108
	v_add_f32_e32 v109, 1.0, v109
	v_add_f32_e32 v110, 1.0, v110
	v_add_f32_e32 v111, 1.0, v111
	v_add_f32_e32 v112, 1.0, v112
	v_add_f32_e32 v113, 1.0, v113
	v_add_f32_e32 v114, 1.0, v114
	v_add_f32_e32 v115, 1.0, v115

.LBB0_1020:
	s_cmp_lt_i32 s78, 10
	s_cselect_b64 s[0:1], -1, 0
	s_cmp_gt_i32 s79, 9
	s_cselect_b64 s[2:3], -1, 0
	s_and_b64 s[0:1], s[0:1], s[2:3]
	s_andn2_b64 vcc, exec, s[0:1]
	s_cbranch_vccnz .LBB0_1081
	s_cmp_lg_u32 s87, 0x100
	s_cbranch_scc1 .Lnr9_orig
	v_mbcnt_hi_u32_b32 v0, -1, v212
	v_and_b32_e32 v0, 63, v0
	v_lshlrev_b32_e32 v1, 5, v0
	v_lshlrev_b32_e32 v2, 4, v0
	v_mov_b32_e32 v9, 0x358637bd
	v_mov_b32_e32 v10, 0x260
	v_xor_b32_e32 v3, 1, v0
	v_lshlrev_b32_e32 v3, 2, v3
	v_xor_b32_e32 v4, 2, v0
	v_lshlrev_b32_e32 v4, 2, v4
	v_xor_b32_e32 v5, 4, v0
	v_lshlrev_b32_e32 v5, 2, v5
	v_xor_b32_e32 v6, 8, v0
	v_lshlrev_b32_e32 v6, 2, v6
	v_xor_b32_e32 v7, 16, v0
	v_lshlrev_b32_e32 v7, 2, v7
	v_xor_b32_e32 v8, 32, v0
	v_lshlrev_b32_e32 v8, 2, v8
	s_lshl_b32 s31, s96, 3
	s_add_u32 s31, s31, s93
	s_add_u32 s64, s76, 0xc989000
	s_addc_u32 s65, s77, 0
	s_add_u32 s66, s76, 0x11189000
	s_addc_u32 s67, s77, 0
	s_add_u32 s68, s76, 0x4a000
	s_addc_u32 s69, s77, 0
	v_readlane_b32 s54, v244, 15
	v_readlane_b32 s55, v244, 16
	s_mov_b32 s23, -1
	s_mul_i32 s5, s31, 9
	s_lshr_b32 s5, s5, 1
	s_add_u32 s41, s31, 1
	s_mul_i32 s41, s41, 9
	s_lshr_b32 s41, s41, 1
	s_nop 0
	s_add_u32 s54, s54, 0x2000
	s_addc_u32 s55, s55, 0
	s_add_u32 s56, s54, 0x1000
	s_addc_u32 s57, s55, 0
	s_cmp_ge_u32 s5, s41
	s_cbranch_scc1 .Lnr9_done
	global_load_dwordx4 v[20:23], v1, s[54:55] offset:0
	global_load_dwordx4 v[24:27], v1, s[54:55] offset:16
	global_load_dwordx4 v[28:31], v1, s[54:55] offset:2048
	global_load_dwordx4 v[32:35], v1, s[54:55] offset:2064
	global_load_dwordx4 v[36:39], v1, s[56:57] offset:0
	global_load_dwordx4 v[40:43], v1, s[56:57] offset:16
	global_load_dwordx4 v[44:47], v1, s[56:57] offset:2048
	global_load_dwordx4 v[48:51], v1, s[56:57] offset:2064
	s_lshl_b32 s35, s5, 13
	s_add_u32 s2, s64, s35
	s_addc_u32 s3, s65, 0
	s_add_u32 s6, s2, 0x1000
	s_addc_u32 s7, s3, 0
	global_load_dwordx4 v[116:119], v1, s[2:3] offset:0
	global_load_dwordx4 v[120:123], v1, s[2:3] offset:16
	global_load_dwordx4 v[124:127], v1, s[2:3] offset:2048
	global_load_dwordx4 v[128:131], v1, s[2:3] offset:2064
	global_load_dwordx4 v[132:135], v1, s[6:7] offset:0
	global_load_dwordx4 v[136:139], v1, s[6:7] offset:16
	global_load_dwordx4 v[140:143], v1, s[6:7] offset:2048
	global_load_dwordx4 v[144:147], v1, s[6:7] offset:2064
	s_waitcnt vmcnt(8)

.LBB0_1397:
	s_cmp_lt_i32 s78, 14
	s_cselect_b64 s[0:1], -1, 0
	s_cmp_gt_i32 s79, 13
	s_cselect_b64 s[2:3], -1, 0
	s_and_b64 s[0:1], s[0:1], s[2:3]
	s_andn2_b64 vcc, exec, s[0:1]
	s_cbranch_vccnz .LBB0_1460
	s_cmp_lg_u32 s87, 0x100
	s_cbranch_scc1 .Lnr13_orig
	v_mbcnt_hi_u32_b32 v0, -1, v212
	v_and_b32_e32 v0, 63, v0
	v_lshlrev_b32_e32 v1, 5, v0
	v_lshlrev_b32_e32 v2, 4, v0
	v_mov_b32_e32 v9, 0x358637bd
	v_mov_b32_e32 v10, 0x260
	v_xor_b32_e32 v3, 1, v0
	v_lshlrev_b32_e32 v3, 2, v3
	v_xor_b32_e32 v4, 2, v0
	v_lshlrev_b32_e32 v4, 2, v4
	v_xor_b32_e32 v5, 4, v0
	v_lshlrev_b32_e32 v5, 2, v5
	v_xor_b32_e32 v6, 8, v0
	v_lshlrev_b32_e32 v6, 2, v6
	v_xor_b32_e32 v7, 16, v0
	v_lshlrev_b32_e32 v7, 2, v7
	v_xor_b32_e32 v8, 32, v0
	v_lshlrev_b32_e32 v8, 2, v8
	s_lshl_b32 s31, s96, 3
	s_add_u32 s31, s31, s93
	s_add_u32 s64, s76, 0xc989000
	s_addc_u32 s65, s77, 0
	s_add_u32 s66, s76, 0x11189000
	s_addc_u32 s67, s77, 0
	s_add_u32 s68, s76, 0x50000
	s_addc_u32 s69, s77, 0
	v_readlane_b32 s54, v244, 17
	v_readlane_b32 s55, v244, 18
	s_mov_b32 s23, -1
	s_lshl_b32 s35, s31, 2
	s_lshr_b32 s25, s35, 11
	s_and_b32 s35, s35, 0x7ff
	s_mul_i32 s5, s25, 0x900
	s_add_u32 s5, s5, s35
	s_add_u32 s5, s5, 0x100
	s_add_u32 s41, s5, 4
	s_nop 0
	s_add_u32 s54, s54, 0x2000
	s_addc_u32 s55, s55, 0
	s_add_u32 s56, s54, 0x1000
	s_addc_u32 s57, s55, 0
	s_cmp_ge_u32 s5, s41
	s_cbranch_scc1 .Lnr13_done
	global_load_dwordx4 v[20:23], v1, s[54:55] offset:0
	global_load_dwordx4 v[24:27], v1, s[54:55] offset:16
	global_load_dwordx4 v[28:31], v1, s[54:55] offset:2048
	global_load_dwordx4 v[32:35], v1, s[54:55] offset:2064
	global_load_dwordx4 v[36:39], v1, s[56:57] offset:0
	global_load_dwordx4 v[40:43], v1, s[56:57] offset:16
	global_load_dwordx4 v[44:47], v1, s[56:57] offset:2048
	global_load_dwordx4 v[48:51], v1, s[56:57] offset:2064
	s_lshl_b32 s35, s5, 13
	s_add_u32 s2, s64, s35
	s_addc_u32 s3, s65, 0
	s_add_u32 s6, s2, 0x1000
	s_addc_u32 s7, s3, 0
	global_load_dwordx4 v[116:119], v1, s[2:3] offset:0
	global_load_dwordx4 v[120:123], v1, s[2:3] offset:16
	global_load_dwordx4 v[124:127], v1, s[2:3] offset:2048
	global_load_dwordx4 v[128:131], v1, s[2:3] offset:2064
	global_load_dwordx4 v[132:135], v1, s[6:7] offset:0
	global_load_dwordx4 v[136:139], v1, s[6:7] offset:16
	global_load_dwordx4 v[140:143], v1, s[6:7] offset:2048
	global_load_dwordx4 v[144:147], v1, s[6:7] offset:2064
	s_waitcnt vmcnt(8)
